# GEMM phases: per-cluster s_setprio flips removed, waves 0-3 run the whole GEMM phase at s_setprio 1
# speedup vs baseline: 1.0118x; 1.0103x over previous
.LBB0_52:
	v_readlane_b32 s100, v255, 2
	s_nop 3
	s_cmp_lt_u32 s100, 4
	s_cbranch_scc0 .Lgprio_1
	s_setprio 1

.LBB0_71:
	ds_read_b128 v[148:151], v157
	ds_read_b128 v[164:167], v157 offset:1024
	ds_read_b128 v[168:171], v157 offset:2048
	ds_read_b128 v[172:175], v157 offset:3072
	ds_read_b128 v[176:179], v158
	ds_read_b128 v[180:183], v158 offset:1024
	ds_read_b128 v[184:187], v158 offset:2048
	ds_read_b128 v[188:191], v158 offset:3072
	s_add_u32 s64, s10, 0xfffc0080
	s_addc_u32 s65, s11, -1
	s_cmp_eq_u32 s47, 12
	s_cselect_b32 s81, s9, s65
	s_cselect_b32 s80, s36, s64
	s_cselect_b32 s79, s37, s46
	s_cselect_b32 s78, s44, s45
	v_lshl_add_u64 v[152:153], s[10:11], 0, v[140:141]
	s_add_i32 m0, s27, 0xc000
	ds_read_b128 v[192:195], v159
	ds_read_b128 v[196:199], v159 offset:1024
	ds_read_b128 v[200:203], v159 offset:2048
	ds_read_b128 v[204:207], v159 offset:3072
	ds_read_b128 v[208:211], v159 offset:4096
	ds_read_b128 v[212:215], v159 offset:5120
	ds_read_b128 v[216:219], v159 offset:6144
	ds_read_b128 v[220:223], v159 offset:7168
	global_load_lds_dwordx4 v[152:153], off
	v_lshl_add_u64 v[152:153], s[10:11], 0, v[142:143]
	s_add_i32 m0, s27, 0xe000
	s_nop 0
	global_load_lds_dwordx4 v[152:153], off
	s_waitcnt vmcnt(8)
	s_waitcnt lgkmcnt(0)
	s_barrier
	s_waitcnt lgkmcnt(0)
	v_mfma_f32_16x16x32_bf16 v[124:127], v[148:151], v[192:195], v[124:127]
	v_mfma_f32_16x16x32_bf16 v[120:123], v[168:171], v[192:195], v[120:123]
	v_mfma_f32_16x16x32_bf16 v[108:111], v[148:151], v[200:203], v[108:111]
	v_mfma_f32_16x16x32_bf16 v[104:107], v[168:171], v[200:203], v[104:107]
	v_mfma_f32_16x16x32_bf16 v[92:95], v[148:151], v[208:211], v[92:95]
	v_mfma_f32_16x16x32_bf16 v[88:91], v[168:171], v[208:211], v[88:91]
	v_mfma_f32_16x16x32_bf16 v[76:79], v[148:151], v[216:219], v[76:79]
	v_mfma_f32_16x16x32_bf16 v[72:75], v[168:171], v[216:219], v[72:75]
	v_mfma_f32_16x16x32_bf16 v[124:127], v[164:167], v[196:199], v[124:127]
	v_mfma_f32_16x16x32_bf16 v[120:123], v[172:175], v[196:199], v[120:123]
	v_mfma_f32_16x16x32_bf16 v[108:111], v[164:167], v[204:207], v[108:111]
	v_mfma_f32_16x16x32_bf16 v[104:107], v[172:175], v[204:207], v[104:107]
	v_mfma_f32_16x16x32_bf16 v[92:95], v[164:167], v[212:215], v[92:95]
	v_mfma_f32_16x16x32_bf16 v[88:91], v[172:175], v[212:215], v[88:91]
	v_mfma_f32_16x16x32_bf16 v[76:79], v[164:167], v[220:223], v[76:79]
	v_mfma_f32_16x16x32_bf16 v[72:75], v[172:175], v[220:223], v[72:75]
	v_mfma_f32_16x16x32_bf16 v[116:119], v[176:179], v[192:195], v[116:119]
	v_mfma_f32_16x16x32_bf16 v[112:115], v[184:187], v[192:195], v[112:115]
	v_mfma_f32_16x16x32_bf16 v[100:103], v[176:179], v[200:203], v[100:103]
	v_mfma_f32_16x16x32_bf16 v[96:99], v[184:187], v[200:203], v[96:99]
	v_mfma_f32_16x16x32_bf16 v[84:87], v[176:179], v[208:211], v[84:87]
	v_mfma_f32_16x16x32_bf16 v[80:83], v[184:187], v[208:211], v[80:83]
	v_mfma_f32_16x16x32_bf16 v[68:71], v[176:179], v[216:219], v[68:71]
	v_mfma_f32_16x16x32_bf16 v[64:67], v[184:187], v[216:219], v[64:67]
	v_mfma_f32_16x16x32_bf16 v[116:119], v[180:183], v[196:199], v[116:119]
	v_mfma_f32_16x16x32_bf16 v[112:115], v[188:191], v[196:199], v[112:115]
	v_mfma_f32_16x16x32_bf16 v[100:103], v[180:183], v[204:207], v[100:103]
	v_mfma_f32_16x16x32_bf16 v[96:99], v[188:191], v[204:207], v[96:99]
	v_mfma_f32_16x16x32_bf16 v[84:87], v[180:183], v[212:215], v[84:87]
	v_mfma_f32_16x16x32_bf16 v[80:83], v[188:191], v[212:215], v[80:83]
	v_mfma_f32_16x16x32_bf16 v[68:71], v[180:183], v[220:223], v[68:71]
	v_mfma_f32_16x16x32_bf16 v[64:67], v[188:191], v[220:223], v[64:67]
	s_barrier
	s_add_i32 s64, s4, s3
	v_lshl_add_u64 v[152:153], s[78:79], 0, v[130:131]
	s_mov_b32 m0, s64
	ds_read_b128 v[192:195], v159 offset:16384
	ds_read_b128 v[196:199], v159 offset:17408
	ds_read_b128 v[200:203], v159 offset:18432
	ds_read_b128 v[204:207], v159 offset:19456
	ds_read_b128 v[208:211], v159 offset:20480
	ds_read_b128 v[212:215], v159 offset:21504
	ds_read_b128 v[216:219], v159 offset:22528
	ds_read_b128 v[220:223], v159 offset:23552
	global_load_lds_dwordx4 v[152:153], off
	s_add_i32 m0, s64, 0x2000
	s_add_u32 s64, s78, 0x40000
	v_lshl_add_u64 v[224:225], s[78:79], 0, v[134:135]
	s_addc_u32 s65, s79, 0
	s_add_i32 s67, s5, s3
	global_load_lds_dwordx4 v[224:225], off
	v_lshl_add_u64 v[226:227], s[64:65], 0, v[130:131]
	s_mov_b32 m0, s67
	v_lshl_add_u64 v[228:229], s[80:81], 0, v[132:133]
	global_load_lds_dwordx4 v[226:227], off
	v_lshl_add_u64 v[226:227], s[64:65], 0, v[134:135]
	s_add_i32 m0, s67, 0x2000
	s_nop 0
	global_load_lds_dwordx4 v[226:227], off
	v_lshl_add_u64 v[226:227], s[80:81], 0, v[128:129]
	s_mov_b32 m0, s27
	s_nop 0
	global_load_lds_dwordx4 v[226:227], off
	s_mov_b32 m0, s90
	s_nop 0
	global_load_lds_dwordx4 v[228:229], off
	s_waitcnt vmcnt(8)
	s_waitcnt lgkmcnt(0)
	s_barrier
	s_waitcnt lgkmcnt(0)
	v_mfma_f32_16x16x32_bf16 v[60:63], v[148:151], v[192:195], v[60:63]
	v_mfma_f32_16x16x32_bf16 v[56:59], v[168:171], v[192:195], v[56:59]
	v_mfma_f32_16x16x32_bf16 v[44:47], v[148:151], v[200:203], v[44:47]
	v_mfma_f32_16x16x32_bf16 v[40:43], v[168:171], v[200:203], v[40:43]
	v_mfma_f32_16x16x32_bf16 v[28:31], v[148:151], v[208:211], v[28:31]
	v_mfma_f32_16x16x32_bf16 v[24:27], v[168:171], v[208:211], v[24:27]
	v_mfma_f32_16x16x32_bf16 v[12:15], v[148:151], v[216:219], v[12:15]
	v_mfma_f32_16x16x32_bf16 v[8:11], v[168:171], v[216:219], v[8:11]
	v_mfma_f32_16x16x32_bf16 v[60:63], v[164:167], v[196:199], v[60:63]
	v_mfma_f32_16x16x32_bf16 v[56:59], v[172:175], v[196:199], v[56:59]
	v_mfma_f32_16x16x32_bf16 v[44:47], v[164:167], v[204:207], v[44:47]
	v_mfma_f32_16x16x32_bf16 v[40:43], v[172:175], v[204:207], v[40:43]
	v_mfma_f32_16x16x32_bf16 v[28:31], v[164:167], v[212:215], v[28:31]
	v_mfma_f32_16x16x32_bf16 v[24:27], v[172:175], v[212:215], v[24:27]
	v_mfma_f32_16x16x32_bf16 v[12:15], v[164:167], v[220:223], v[12:15]
	v_mfma_f32_16x16x32_bf16 v[8:11], v[172:175], v[220:223], v[8:11]
	v_mfma_f32_16x16x32_bf16 v[52:55], v[176:179], v[192:195], v[52:55]
	v_mfma_f32_16x16x32_bf16 v[48:51], v[184:187], v[192:195], v[48:51]
	v_mfma_f32_16x16x32_bf16 v[36:39], v[176:179], v[200:203], v[36:39]
	v_mfma_f32_16x16x32_bf16 v[32:35], v[184:187], v[200:203], v[32:35]
	v_mfma_f32_16x16x32_bf16 v[20:23], v[176:179], v[208:211], v[20:23]
	v_mfma_f32_16x16x32_bf16 v[16:19], v[184:187], v[208:211], v[16:19]
	v_mfma_f32_16x16x32_bf16 v[4:7], v[176:179], v[216:219], v[4:7]
	v_mfma_f32_16x16x32_bf16 v[0:3], v[184:187], v[216:219], v[0:3]
	v_mfma_f32_16x16x32_bf16 v[52:55], v[180:183], v[196:199], v[52:55]
	v_mfma_f32_16x16x32_bf16 v[48:51], v[188:191], v[196:199], v[48:51]
	v_mfma_f32_16x16x32_bf16 v[36:39], v[180:183], v[204:207], v[36:39]
	v_mfma_f32_16x16x32_bf16 v[32:35], v[188:191], v[204:207], v[32:35]
	v_mfma_f32_16x16x32_bf16 v[20:23], v[180:183], v[212:215], v[20:23]
	v_mfma_f32_16x16x32_bf16 v[16:19], v[188:191], v[212:215], v[16:19]
	v_mfma_f32_16x16x32_bf16 v[4:7], v[180:183], v[220:223], v[4:7]
	v_mfma_f32_16x16x32_bf16 v[0:3], v[188:191], v[220:223], v[0:3]
	s_barrier
	s_add_i32 s67, 0, 0x18000
	v_add_u32_e32 v136, s67, v155
	s_add_i32 s71, 0, 0x1c000
	ds_read_b128 v[148:151], v136
	ds_read_b128 v[164:167], v136 offset:1024
	ds_read_b128 v[168:171], v136 offset:2048
	ds_read_b128 v[172:175], v136 offset:3072
	v_add_u32_e32 v136, s71, v155
	ds_read_b128 v[176:179], v136
	ds_read_b128 v[180:183], v136 offset:1024
	ds_read_b128 v[184:187], v136 offset:2048
	ds_read_b128 v[188:191], v136 offset:3072
	s_add_u32 s64, s80, 0x40000
	s_addc_u32 s65, s81, 0
	s_mov_b32 m0, s91
	v_lshl_add_u64 v[230:231], s[64:65], 0, v[128:129]
	ds_read_b128 v[192:195], v159 offset:32768
	ds_read_b128 v[196:199], v159 offset:33792
	ds_read_b128 v[200:203], v159 offset:34816
	ds_read_b128 v[204:207], v159 offset:35840
	ds_read_b128 v[208:211], v159 offset:36864
	ds_read_b128 v[212:215], v159 offset:37888
	ds_read_b128 v[216:219], v159 offset:38912
	ds_read_b128 v[220:223], v159 offset:39936
	global_load_lds_dwordx4 v[230:231], off
	v_lshl_add_u64 v[230:231], s[64:65], 0, v[132:133]
	s_mov_b32 m0, s92
	s_nop 0
	global_load_lds_dwordx4 v[230:231], off
	s_waitcnt vmcnt(8)
	s_waitcnt lgkmcnt(0)
	s_barrier
	s_waitcnt lgkmcnt(0)
	v_mfma_f32_16x16x32_bf16 v[124:127], v[148:151], v[192:195], v[124:127]
	v_mfma_f32_16x16x32_bf16 v[120:123], v[168:171], v[192:195], v[120:123]
	v_mfma_f32_16x16x32_bf16 v[108:111], v[148:151], v[200:203], v[108:111]
	v_mfma_f32_16x16x32_bf16 v[104:107], v[168:171], v[200:203], v[104:107]
	v_mfma_f32_16x16x32_bf16 v[92:95], v[148:151], v[208:211], v[92:95]
	v_mfma_f32_16x16x32_bf16 v[88:91], v[168:171], v[208:211], v[88:91]
	v_mfma_f32_16x16x32_bf16 v[76:79], v[148:151], v[216:219], v[76:79]
	v_mfma_f32_16x16x32_bf16 v[72:75], v[168:171], v[216:219], v[72:75]
	v_mfma_f32_16x16x32_bf16 v[124:127], v[164:167], v[196:199], v[124:127]
	v_mfma_f32_16x16x32_bf16 v[120:123], v[172:175], v[196:199], v[120:123]
	v_mfma_f32_16x16x32_bf16 v[108:111], v[164:167], v[204:207], v[108:111]
	v_mfma_f32_16x16x32_bf16 v[104:107], v[172:175], v[204:207], v[104:107]
	v_mfma_f32_16x16x32_bf16 v[92:95], v[164:167], v[212:215], v[92:95]
	v_mfma_f32_16x16x32_bf16 v[88:91], v[172:175], v[212:215], v[88:91]
	v_mfma_f32_16x16x32_bf16 v[76:79], v[164:167], v[220:223], v[76:79]
	v_mfma_f32_16x16x32_bf16 v[72:75], v[172:175], v[220:223], v[72:75]
	v_mfma_f32_16x16x32_bf16 v[116:119], v[176:179], v[192:195], v[116:119]
	v_mfma_f32_16x16x32_bf16 v[112:115], v[184:187], v[192:195], v[112:115]
	v_mfma_f32_16x16x32_bf16 v[100:103], v[176:179], v[200:203], v[100:103]
	v_mfma_f32_16x16x32_bf16 v[96:99], v[184:187], v[200:203], v[96:99]
	v_mfma_f32_16x16x32_bf16 v[84:87], v[176:179], v[208:211], v[84:87]
	v_mfma_f32_16x16x32_bf16 v[80:83], v[184:187], v[208:211], v[80:83]
	v_mfma_f32_16x16x32_bf16 v[68:71], v[176:179], v[216:219], v[68:71]
	v_mfma_f32_16x16x32_bf16 v[64:67], v[184:187], v[216:219], v[64:67]
	v_mfma_f32_16x16x32_bf16 v[116:119], v[180:183], v[196:199], v[116:119]
	v_mfma_f32_16x16x32_bf16 v[112:115], v[188:191], v[196:199], v[112:115]
	v_mfma_f32_16x16x32_bf16 v[100:103], v[180:183], v[204:207], v[100:103]
	v_mfma_f32_16x16x32_bf16 v[96:99], v[188:191], v[204:207], v[96:99]
	v_mfma_f32_16x16x32_bf16 v[84:87], v[180:183], v[212:215], v[84:87]
	v_mfma_f32_16x16x32_bf16 v[80:83], v[188:191], v[212:215], v[80:83]
	v_mfma_f32_16x16x32_bf16 v[68:71], v[180:183], v[220:223], v[68:71]
	v_mfma_f32_16x16x32_bf16 v[64:67], v[188:191], v[220:223], v[64:67]
	s_barrier
	s_add_i32 s64, s67, s3
	v_lshl_add_u64 v[152:153], v[152:153], 0, s[40:41]
	s_mov_b32 m0, s64
	ds_read_b128 v[192:195], v159 offset:49152
	ds_read_b128 v[196:199], v159 offset:50176
	ds_read_b128 v[200:203], v159 offset:51200
	ds_read_b128 v[204:207], v159 offset:52224
	ds_read_b128 v[208:211], v159 offset:53248
	ds_read_b128 v[212:215], v159 offset:54272
	ds_read_b128 v[216:219], v159 offset:55296
	ds_read_b128 v[220:223], v159 offset:56320
	global_load_lds_dwordx4 v[152:153], off
	s_add_i32 m0, s64, 0x2000
	s_add_u32 s64, s78, 0x40080
	v_lshl_add_u64 v[152:153], v[224:225], 0, s[40:41]
	s_addc_u32 s65, s79, 0
	s_add_i32 s67, s71, s3
	global_load_lds_dwordx4 v[152:153], off
	v_lshl_add_u64 v[152:153], s[64:65], 0, v[130:131]
	s_mov_b32 m0, s67
	s_nop 0
	global_load_lds_dwordx4 v[152:153], off
	v_lshl_add_u64 v[152:153], s[64:65], 0, v[134:135]
	s_add_i32 m0, s67, 0x2000
	s_nop 0
	global_load_lds_dwordx4 v[152:153], off
	v_lshl_add_u64 v[152:153], v[226:227], 0, s[40:41]
	s_mov_b32 m0, s94
	s_nop 0
	global_load_lds_dwordx4 v[152:153], off
	v_lshl_add_u64 v[152:153], v[228:229], 0, s[40:41]
	s_mov_b32 m0, s95
	s_nop 0
	global_load_lds_dwordx4 v[152:153], off
	s_waitcnt vmcnt(8)
	s_waitcnt lgkmcnt(0)
	s_barrier
	s_waitcnt lgkmcnt(0)
	v_mfma_f32_16x16x32_bf16 v[60:63], v[148:151], v[192:195], v[60:63]
	v_mfma_f32_16x16x32_bf16 v[56:59], v[168:171], v[192:195], v[56:59]
	v_mfma_f32_16x16x32_bf16 v[44:47], v[148:151], v[200:203], v[44:47]
	v_mfma_f32_16x16x32_bf16 v[40:43], v[168:171], v[200:203], v[40:43]
	v_mfma_f32_16x16x32_bf16 v[28:31], v[148:151], v[208:211], v[28:31]
	v_mfma_f32_16x16x32_bf16 v[24:27], v[168:171], v[208:211], v[24:27]
	v_mfma_f32_16x16x32_bf16 v[12:15], v[148:151], v[216:219], v[12:15]
	v_mfma_f32_16x16x32_bf16 v[8:11], v[168:171], v[216:219], v[8:11]
	v_mfma_f32_16x16x32_bf16 v[60:63], v[164:167], v[196:199], v[60:63]
	v_mfma_f32_16x16x32_bf16 v[56:59], v[172:175], v[196:199], v[56:59]
	v_mfma_f32_16x16x32_bf16 v[44:47], v[164:167], v[204:207], v[44:47]
	v_mfma_f32_16x16x32_bf16 v[40:43], v[172:175], v[204:207], v[40:43]
	v_mfma_f32_16x16x32_bf16 v[28:31], v[164:167], v[212:215], v[28:31]
	v_mfma_f32_16x16x32_bf16 v[24:27], v[172:175], v[212:215], v[24:27]
	v_mfma_f32_16x16x32_bf16 v[12:15], v[164:167], v[220:223], v[12:15]
	v_mfma_f32_16x16x32_bf16 v[8:11], v[172:175], v[220:223], v[8:11]
	v_mfma_f32_16x16x32_bf16 v[52:55], v[176:179], v[192:195], v[52:55]
	v_mfma_f32_16x16x32_bf16 v[48:51], v[184:187], v[192:195], v[48:51]
	v_mfma_f32_16x16x32_bf16 v[36:39], v[176:179], v[200:203], v[36:39]
	v_mfma_f32_16x16x32_bf16 v[32:35], v[184:187], v[200:203], v[32:35]
	v_mfma_f32_16x16x32_bf16 v[20:23], v[176:179], v[208:211], v[20:23]
	v_mfma_f32_16x16x32_bf16 v[16:19], v[184:187], v[208:211], v[16:19]
	v_mfma_f32_16x16x32_bf16 v[4:7], v[176:179], v[216:219], v[4:7]
	v_mfma_f32_16x16x32_bf16 v[0:3], v[184:187], v[216:219], v[0:3]
	v_mfma_f32_16x16x32_bf16 v[52:55], v[180:183], v[196:199], v[52:55]
	v_mfma_f32_16x16x32_bf16 v[48:51], v[188:191], v[196:199], v[48:51]
	v_mfma_f32_16x16x32_bf16 v[36:39], v[180:183], v[204:207], v[36:39]
	v_mfma_f32_16x16x32_bf16 v[32:35], v[188:191], v[204:207], v[32:35]
	v_mfma_f32_16x16x32_bf16 v[20:23], v[180:183], v[212:215], v[20:23]
	v_mfma_f32_16x16x32_bf16 v[16:19], v[188:191], v[212:215], v[16:19]
	v_mfma_f32_16x16x32_bf16 v[4:7], v[180:183], v[220:223], v[4:7]
	v_mfma_f32_16x16x32_bf16 v[0:3], v[188:191], v[220:223], v[0:3]
	s_barrier
	s_add_i32 s47, s47, 2
	s_add_u32 s10, s10, 0x100
	s_addc_u32 s11, s11, 0
	s_add_u32 s45, s45, 0x100
	s_addc_u32 s46, s46, 0
	s_cmp_gt_u32 s47, 13
	s_cbranch_scc0 .LBB0_71
	s_and_b64 vcc, exec, s[42:43]
	s_cbranch_vccz .LBB0_74
	s_barrier

.LBB0_226:
	s_setprio 0
	v_writelane_b32 v255, s4, 28
	v_mov_b32_e32 v3, 0
	s_mov_b64 s[6:7], 0
	v_writelane_b32 v255, s5, 29
	v_mov_b32_e32 v0, 0
	v_mov_b32_e32 v1, v3
	s_barrier
	v_mbcnt_lo_u32_b32 v2, -1, 0
	v_mbcnt_hi_u32_b32 v2, -1, v2

.LBB0_293:
	ds_read_b128 v[150:153], v147
	ds_read_b128 v[154:157], v147 offset:1024
	ds_read_b128 v[158:161], v147 offset:2048
	ds_read_b128 v[162:165], v147 offset:3072
	ds_read_b128 v[166:169], v148
	ds_read_b128 v[170:173], v148 offset:1024
	ds_read_b128 v[174:177], v148 offset:2048
	ds_read_b128 v[178:181], v148 offset:3072
	s_add_u32 s40, s24, 0xfff00080
	s_addc_u32 s41, s25, -1
	s_cmp_eq_u32 s64, 12
	s_cselect_b32 s43, s17, s41
	s_cselect_b32 s42, s48, s40
	s_cselect_b32 s41, s15, s51
	s_cselect_b32 s40, s49, s50
	v_lshl_add_u64 v[214:215], s[24:25], 0, v[136:137]
	s_add_i32 m0, s5, 0xc000
	ds_read_b128 v[182:185], v149
	ds_read_b128 v[186:189], v149 offset:1024
	ds_read_b128 v[190:193], v149 offset:2048
	ds_read_b128 v[194:197], v149 offset:3072
	ds_read_b128 v[198:201], v149 offset:4096
	ds_read_b128 v[202:205], v149 offset:5120
	ds_read_b128 v[206:209], v149 offset:6144
	ds_read_b128 v[210:213], v149 offset:7168
	global_load_lds_dwordx4 v[214:215], off
	v_lshl_add_u64 v[214:215], s[24:25], 0, v[138:139]
	s_add_i32 m0, s5, 0xe000
	s_nop 0
	global_load_lds_dwordx4 v[214:215], off
	s_waitcnt vmcnt(8)
	s_waitcnt lgkmcnt(0)
	s_barrier
	s_waitcnt lgkmcnt(0)
	v_mfma_f32_16x16x32_bf16 v[124:127], v[150:153], v[182:185], v[124:127]
	v_mfma_f32_16x16x32_bf16 v[120:123], v[158:161], v[182:185], v[120:123]
	v_mfma_f32_16x16x32_bf16 v[116:119], v[150:153], v[190:193], v[116:119]
	v_mfma_f32_16x16x32_bf16 v[112:115], v[158:161], v[190:193], v[112:115]
	v_mfma_f32_16x16x32_bf16 v[100:103], v[150:153], v[198:201], v[100:103]
	v_mfma_f32_16x16x32_bf16 v[96:99], v[158:161], v[198:201], v[96:99]
	v_mfma_f32_16x16x32_bf16 v[84:87], v[150:153], v[206:209], v[84:87]
	v_mfma_f32_16x16x32_bf16 v[80:83], v[158:161], v[206:209], v[80:83]
	v_mfma_f32_16x16x32_bf16 v[124:127], v[154:157], v[186:189], v[124:127]
	v_mfma_f32_16x16x32_bf16 v[120:123], v[162:165], v[186:189], v[120:123]
	v_mfma_f32_16x16x32_bf16 v[116:119], v[154:157], v[194:197], v[116:119]
	v_mfma_f32_16x16x32_bf16 v[112:115], v[162:165], v[194:197], v[112:115]
	v_mfma_f32_16x16x32_bf16 v[100:103], v[154:157], v[202:205], v[100:103]
	v_mfma_f32_16x16x32_bf16 v[96:99], v[162:165], v[202:205], v[96:99]
	v_mfma_f32_16x16x32_bf16 v[84:87], v[154:157], v[210:213], v[84:87]
	v_mfma_f32_16x16x32_bf16 v[80:83], v[162:165], v[210:213], v[80:83]
	v_mfma_f32_16x16x32_bf16 v[108:111], v[166:169], v[182:185], v[108:111]
	v_mfma_f32_16x16x32_bf16 v[104:107], v[174:177], v[182:185], v[104:107]
	v_mfma_f32_16x16x32_bf16 v[92:95], v[166:169], v[190:193], v[92:95]
	v_mfma_f32_16x16x32_bf16 v[88:91], v[174:177], v[190:193], v[88:91]
	v_mfma_f32_16x16x32_bf16 v[76:79], v[166:169], v[198:201], v[76:79]
	v_mfma_f32_16x16x32_bf16 v[72:75], v[174:177], v[198:201], v[72:75]
	v_mfma_f32_16x16x32_bf16 v[68:71], v[166:169], v[206:209], v[68:71]
	v_mfma_f32_16x16x32_bf16 v[64:67], v[174:177], v[206:209], v[64:67]
	v_mfma_f32_16x16x32_bf16 v[108:111], v[170:173], v[186:189], v[108:111]
	v_mfma_f32_16x16x32_bf16 v[104:107], v[178:181], v[186:189], v[104:107]
	v_mfma_f32_16x16x32_bf16 v[92:95], v[170:173], v[194:197], v[92:95]
	v_mfma_f32_16x16x32_bf16 v[88:91], v[178:181], v[194:197], v[88:91]
	v_mfma_f32_16x16x32_bf16 v[76:79], v[170:173], v[202:205], v[76:79]
	v_mfma_f32_16x16x32_bf16 v[72:75], v[178:181], v[202:205], v[72:75]
	v_mfma_f32_16x16x32_bf16 v[68:71], v[170:173], v[210:213], v[68:71]
	v_mfma_f32_16x16x32_bf16 v[64:67], v[178:181], v[210:213], v[64:67]
	s_barrier
	s_add_i32 s65, s45, s3
	v_lshl_add_u64 v[214:215], s[40:41], 0, v[130:131]
	s_mov_b32 m0, s65
	ds_read_b128 v[182:185], v149 offset:16384
	ds_read_b128 v[186:189], v149 offset:17408
	ds_read_b128 v[190:193], v149 offset:18432
	ds_read_b128 v[194:197], v149 offset:19456
	ds_read_b128 v[198:201], v149 offset:20480
	ds_read_b128 v[202:205], v149 offset:21504
	ds_read_b128 v[206:209], v149 offset:22528
	ds_read_b128 v[210:213], v149 offset:23552
	global_load_lds_dwordx4 v[214:215], off
	s_add_i32 m0, s65, 0x2000
	s_add_u32 s68, s40, 0x40000
	v_lshl_add_u64 v[218:219], s[40:41], 0, v[134:135]
	s_addc_u32 s69, s41, 0
	s_add_i32 s65, s46, s3
	global_load_lds_dwordx4 v[218:219], off
	v_lshl_add_u64 v[220:221], s[68:69], 0, v[130:131]
	s_mov_b32 m0, s65
	v_lshl_add_u64 v[222:223], s[42:43], 0, v[132:133]
	global_load_lds_dwordx4 v[220:221], off
	v_lshl_add_u64 v[220:221], s[68:69], 0, v[134:135]
	s_add_i32 m0, s65, 0x2000
	s_nop 0
	global_load_lds_dwordx4 v[220:221], off
	v_lshl_add_u64 v[220:221], s[42:43], 0, v[128:129]
	s_mov_b32 m0, s5
	s_nop 0
	global_load_lds_dwordx4 v[220:221], off
	s_mov_b32 m0, s13
	s_nop 0
	global_load_lds_dwordx4 v[222:223], off
	s_waitcnt vmcnt(8)
	s_waitcnt lgkmcnt(0)
	s_barrier
	s_waitcnt lgkmcnt(0)
	v_mfma_f32_16x16x32_bf16 v[60:63], v[150:153], v[182:185], v[60:63]
	v_mfma_f32_16x16x32_bf16 v[56:59], v[158:161], v[182:185], v[56:59]
	v_mfma_f32_16x16x32_bf16 v[52:55], v[150:153], v[190:193], v[52:55]
	v_mfma_f32_16x16x32_bf16 v[48:51], v[158:161], v[190:193], v[48:51]
	v_mfma_f32_16x16x32_bf16 v[36:39], v[150:153], v[198:201], v[36:39]
	v_mfma_f32_16x16x32_bf16 v[32:35], v[158:161], v[198:201], v[32:35]
	v_mfma_f32_16x16x32_bf16 v[20:23], v[150:153], v[206:209], v[20:23]
	v_mfma_f32_16x16x32_bf16 v[16:19], v[158:161], v[206:209], v[16:19]
	v_mfma_f32_16x16x32_bf16 v[60:63], v[154:157], v[186:189], v[60:63]
	v_mfma_f32_16x16x32_bf16 v[56:59], v[162:165], v[186:189], v[56:59]
	v_mfma_f32_16x16x32_bf16 v[52:55], v[154:157], v[194:197], v[52:55]
	v_mfma_f32_16x16x32_bf16 v[48:51], v[162:165], v[194:197], v[48:51]
	v_mfma_f32_16x16x32_bf16 v[36:39], v[154:157], v[202:205], v[36:39]
	v_mfma_f32_16x16x32_bf16 v[32:35], v[162:165], v[202:205], v[32:35]
	v_mfma_f32_16x16x32_bf16 v[20:23], v[154:157], v[210:213], v[20:23]
	v_mfma_f32_16x16x32_bf16 v[16:19], v[162:165], v[210:213], v[16:19]
	v_mfma_f32_16x16x32_bf16 v[44:47], v[166:169], v[182:185], v[44:47]
	v_mfma_f32_16x16x32_bf16 v[40:43], v[174:177], v[182:185], v[40:43]
	v_mfma_f32_16x16x32_bf16 v[28:31], v[166:169], v[190:193], v[28:31]
	v_mfma_f32_16x16x32_bf16 v[24:27], v[174:177], v[190:193], v[24:27]
	v_mfma_f32_16x16x32_bf16 v[12:15], v[166:169], v[198:201], v[12:15]
	v_mfma_f32_16x16x32_bf16 v[8:11], v[174:177], v[198:201], v[8:11]
	v_mfma_f32_16x16x32_bf16 v[4:7], v[166:169], v[206:209], v[4:7]
	v_mfma_f32_16x16x32_bf16 v[0:3], v[174:177], v[206:209], v[0:3]
	v_mfma_f32_16x16x32_bf16 v[44:47], v[170:173], v[186:189], v[44:47]
	v_mfma_f32_16x16x32_bf16 v[40:43], v[178:181], v[186:189], v[40:43]
	v_mfma_f32_16x16x32_bf16 v[28:31], v[170:173], v[194:197], v[28:31]
	v_mfma_f32_16x16x32_bf16 v[24:27], v[178:181], v[194:197], v[24:27]
	v_mfma_f32_16x16x32_bf16 v[12:15], v[170:173], v[202:205], v[12:15]
	v_mfma_f32_16x16x32_bf16 v[8:11], v[178:181], v[202:205], v[8:11]
	v_mfma_f32_16x16x32_bf16 v[4:7], v[170:173], v[210:213], v[4:7]
	v_mfma_f32_16x16x32_bf16 v[0:3], v[178:181], v[210:213], v[0:3]
	s_barrier
	s_add_i32 s65, 0, 0x18000
	v_add_u32_e32 v162, s65, v145
	v_add_u32_e32 v178, s72, v145
	ds_read_b128 v[150:153], v162
	ds_read_b128 v[154:157], v162 offset:1024
	ds_read_b128 v[158:161], v162 offset:2048
	ds_read_b128 v[162:165], v162 offset:3072
	ds_read_b128 v[166:169], v178
	ds_read_b128 v[170:173], v178 offset:1024
	ds_read_b128 v[174:177], v178 offset:2048
	ds_read_b128 v[178:181], v178 offset:3072
	s_add_u32 s42, s42, 0x100000
	s_addc_u32 s43, s43, 0
	s_mov_b32 m0, s27
	v_lshl_add_u64 v[224:225], s[42:43], 0, v[128:129]
	ds_read_b128 v[182:185], v149 offset:32768
	ds_read_b128 v[186:189], v149 offset:33792
	ds_read_b128 v[190:193], v149 offset:34816
	ds_read_b128 v[194:197], v149 offset:35840
	ds_read_b128 v[198:201], v149 offset:36864
	ds_read_b128 v[202:205], v149 offset:37888
	ds_read_b128 v[206:209], v149 offset:38912
	ds_read_b128 v[210:213], v149 offset:39936
	global_load_lds_dwordx4 v[224:225], off
	v_lshl_add_u64 v[224:225], s[42:43], 0, v[132:133]
	s_mov_b32 m0, s36
	s_nop 0
	global_load_lds_dwordx4 v[224:225], off
	s_waitcnt vmcnt(8)
	s_waitcnt lgkmcnt(0)
	s_barrier
	s_waitcnt lgkmcnt(0)
	v_mfma_f32_16x16x32_bf16 v[124:127], v[150:153], v[182:185], v[124:127]
	v_mfma_f32_16x16x32_bf16 v[120:123], v[158:161], v[182:185], v[120:123]
	v_mfma_f32_16x16x32_bf16 v[116:119], v[150:153], v[190:193], v[116:119]
	v_mfma_f32_16x16x32_bf16 v[112:115], v[158:161], v[190:193], v[112:115]
	v_mfma_f32_16x16x32_bf16 v[100:103], v[150:153], v[198:201], v[100:103]
	v_mfma_f32_16x16x32_bf16 v[96:99], v[158:161], v[198:201], v[96:99]
	v_mfma_f32_16x16x32_bf16 v[84:87], v[150:153], v[206:209], v[84:87]
	v_mfma_f32_16x16x32_bf16 v[80:83], v[158:161], v[206:209], v[80:83]
	v_mfma_f32_16x16x32_bf16 v[124:127], v[154:157], v[186:189], v[124:127]
	v_mfma_f32_16x16x32_bf16 v[120:123], v[162:165], v[186:189], v[120:123]
	v_mfma_f32_16x16x32_bf16 v[116:119], v[154:157], v[194:197], v[116:119]
	v_mfma_f32_16x16x32_bf16 v[112:115], v[162:165], v[194:197], v[112:115]
	v_mfma_f32_16x16x32_bf16 v[100:103], v[154:157], v[202:205], v[100:103]
	v_mfma_f32_16x16x32_bf16 v[96:99], v[162:165], v[202:205], v[96:99]
	v_mfma_f32_16x16x32_bf16 v[84:87], v[154:157], v[210:213], v[84:87]
	v_mfma_f32_16x16x32_bf16 v[80:83], v[162:165], v[210:213], v[80:83]
	v_mfma_f32_16x16x32_bf16 v[108:111], v[166:169], v[182:185], v[108:111]
	v_mfma_f32_16x16x32_bf16 v[104:107], v[174:177], v[182:185], v[104:107]
	v_mfma_f32_16x16x32_bf16 v[92:95], v[166:169], v[190:193], v[92:95]
	v_mfma_f32_16x16x32_bf16 v[88:91], v[174:177], v[190:193], v[88:91]
	v_mfma_f32_16x16x32_bf16 v[76:79], v[166:169], v[198:201], v[76:79]
	v_mfma_f32_16x16x32_bf16 v[72:75], v[174:177], v[198:201], v[72:75]
	v_mfma_f32_16x16x32_bf16 v[68:71], v[166:169], v[206:209], v[68:71]
	v_mfma_f32_16x16x32_bf16 v[64:67], v[174:177], v[206:209], v[64:67]
	v_mfma_f32_16x16x32_bf16 v[108:111], v[170:173], v[186:189], v[108:111]
	v_mfma_f32_16x16x32_bf16 v[104:107], v[178:181], v[186:189], v[104:107]
	v_mfma_f32_16x16x32_bf16 v[92:95], v[170:173], v[194:197], v[92:95]
	v_mfma_f32_16x16x32_bf16 v[88:91], v[178:181], v[194:197], v[88:91]
	v_mfma_f32_16x16x32_bf16 v[76:79], v[170:173], v[202:205], v[76:79]
	v_mfma_f32_16x16x32_bf16 v[72:75], v[178:181], v[202:205], v[72:75]
	v_mfma_f32_16x16x32_bf16 v[68:71], v[170:173], v[210:213], v[68:71]
	v_mfma_f32_16x16x32_bf16 v[64:67], v[178:181], v[210:213], v[64:67]
	s_barrier
	s_add_i32 s42, s65, s3
	v_lshl_add_u64 v[214:215], v[214:215], 0, s[10:11]
	s_mov_b32 m0, s42
	ds_read_b128 v[182:185], v149 offset:49152
	ds_read_b128 v[186:189], v149 offset:50176
	ds_read_b128 v[190:193], v149 offset:51200
	ds_read_b128 v[194:197], v149 offset:52224
	ds_read_b128 v[198:201], v149 offset:53248
	ds_read_b128 v[202:205], v149 offset:54272
	ds_read_b128 v[206:209], v149 offset:55296
	ds_read_b128 v[210:213], v149 offset:56320
	global_load_lds_dwordx4 v[214:215], off
	s_add_i32 m0, s42, 0x2000
	s_add_u32 s40, s40, 0x40080
	v_lshl_add_u64 v[214:215], v[218:219], 0, s[10:11]
	s_addc_u32 s41, s41, 0
	s_add_i32 s42, s72, s3
	global_load_lds_dwordx4 v[214:215], off
	v_lshl_add_u64 v[214:215], s[40:41], 0, v[130:131]
	s_mov_b32 m0, s42
	s_nop 0
	global_load_lds_dwordx4 v[214:215], off
	v_lshl_add_u64 v[214:215], s[40:41], 0, v[134:135]
	s_add_i32 m0, s42, 0x2000
	s_nop 0
	global_load_lds_dwordx4 v[214:215], off
	v_lshl_add_u64 v[214:215], v[220:221], 0, s[10:11]
	s_mov_b32 m0, s38
	s_nop 0
	global_load_lds_dwordx4 v[214:215], off
	v_lshl_add_u64 v[214:215], v[222:223], 0, s[10:11]
	s_mov_b32 m0, s39
	s_nop 0
	global_load_lds_dwordx4 v[214:215], off
	s_waitcnt vmcnt(8)
	s_waitcnt lgkmcnt(0)
	s_barrier
	s_waitcnt lgkmcnt(0)
	v_mfma_f32_16x16x32_bf16 v[60:63], v[150:153], v[182:185], v[60:63]
	v_mfma_f32_16x16x32_bf16 v[56:59], v[158:161], v[182:185], v[56:59]
	v_mfma_f32_16x16x32_bf16 v[52:55], v[150:153], v[190:193], v[52:55]
	v_mfma_f32_16x16x32_bf16 v[48:51], v[158:161], v[190:193], v[48:51]
	v_mfma_f32_16x16x32_bf16 v[36:39], v[150:153], v[198:201], v[36:39]
	v_mfma_f32_16x16x32_bf16 v[32:35], v[158:161], v[198:201], v[32:35]
	v_mfma_f32_16x16x32_bf16 v[20:23], v[150:153], v[206:209], v[20:23]
	v_mfma_f32_16x16x32_bf16 v[16:19], v[158:161], v[206:209], v[16:19]
	v_mfma_f32_16x16x32_bf16 v[60:63], v[154:157], v[186:189], v[60:63]
	v_mfma_f32_16x16x32_bf16 v[56:59], v[162:165], v[186:189], v[56:59]
	v_mfma_f32_16x16x32_bf16 v[52:55], v[154:157], v[194:197], v[52:55]
	v_mfma_f32_16x16x32_bf16 v[48:51], v[162:165], v[194:197], v[48:51]
	v_mfma_f32_16x16x32_bf16 v[36:39], v[154:157], v[202:205], v[36:39]
	v_mfma_f32_16x16x32_bf16 v[32:35], v[162:165], v[202:205], v[32:35]
	v_mfma_f32_16x16x32_bf16 v[20:23], v[154:157], v[210:213], v[20:23]
	v_mfma_f32_16x16x32_bf16 v[16:19], v[162:165], v[210:213], v[16:19]
	v_mfma_f32_16x16x32_bf16 v[44:47], v[166:169], v[182:185], v[44:47]
	v_mfma_f32_16x16x32_bf16 v[40:43], v[174:177], v[182:185], v[40:43]
	v_mfma_f32_16x16x32_bf16 v[28:31], v[166:169], v[190:193], v[28:31]
	v_mfma_f32_16x16x32_bf16 v[24:27], v[174:177], v[190:193], v[24:27]
	v_mfma_f32_16x16x32_bf16 v[12:15], v[166:169], v[198:201], v[12:15]
	v_mfma_f32_16x16x32_bf16 v[8:11], v[174:177], v[198:201], v[8:11]
	v_mfma_f32_16x16x32_bf16 v[4:7], v[166:169], v[206:209], v[4:7]
	v_mfma_f32_16x16x32_bf16 v[0:3], v[174:177], v[206:209], v[0:3]
	v_mfma_f32_16x16x32_bf16 v[44:47], v[170:173], v[186:189], v[44:47]
	v_mfma_f32_16x16x32_bf16 v[40:43], v[178:181], v[186:189], v[40:43]
	v_mfma_f32_16x16x32_bf16 v[28:31], v[170:173], v[194:197], v[28:31]
	v_mfma_f32_16x16x32_bf16 v[24:27], v[178:181], v[194:197], v[24:27]
	v_mfma_f32_16x16x32_bf16 v[12:15], v[170:173], v[202:205], v[12:15]
	v_mfma_f32_16x16x32_bf16 v[8:11], v[178:181], v[202:205], v[8:11]
	v_mfma_f32_16x16x32_bf16 v[4:7], v[170:173], v[210:213], v[4:7]
	v_mfma_f32_16x16x32_bf16 v[0:3], v[178:181], v[210:213], v[0:3]
	s_barrier
	s_add_i32 s64, s64, 2
	s_add_u32 s24, s24, 0x100
	s_addc_u32 s25, s25, 0
	s_add_u32 s50, s50, 0x100
	s_addc_u32 s51, s51, 0
	s_cmp_gt_u32 s64, 13
	s_cbranch_scc0 .LBB0_293
	s_and_b64 vcc, exec, s[28:29]
	s_cbranch_vccz .LBB0_296
	s_barrier

.LBB0_308:
	s_setprio 0
	v_readlane_b32 s0, v255, 19
	v_readlane_b32 s1, v255, 20
	s_andn2_b64 vcc, exec, s[0:1]
	s_nop 0
	v_cndmask_b32_e64 v0, 0, 1, s[0:1]
	v_cmp_ne_u32_e64 s[8:9], 1, v0
	s_barrier
	v_mbcnt_lo_u32_b32 v0, -1, 0
	v_mbcnt_hi_u32_b32 v0, -1, v0
	s_cbranch_vccnz .LBB0_313
	v_lshlrev_b32_e32 v16, 2, v0
	v_and_b32_e32 v0, 64, v254
	v_add_u32_e32 v0, 64, v0
	v_xor_b32_e32 v1, 32, v254
	v_cmp_lt_i32_e32 vcc, v1, v0
	v_ashrrev_i32_e32 v17, 31, v16
	v_readlane_b32 s36, v255, 3
	v_cndmask_b32_e32 v1, v254, v1, vcc
	v_lshlrev_b32_e32 v48, 2, v1
	v_xor_b32_e32 v1, 16, v254
	v_cmp_lt_i32_e32 vcc, v1, v0
	v_lshlrev_b64 v[22:23], 2, v[16:17]
	v_readlane_b32 s44, v255, 11
	v_cndmask_b32_e32 v1, v254, v1, vcc
	v_lshlrev_b32_e32 v49, 2, v1
	v_xor_b32_e32 v1, 8, v254
	v_cmp_lt_i32_e32 vcc, v1, v0
	v_readlane_b32 s45, v255, 12
	s_mov_b64 s[0:1], 0x1000
	v_cndmask_b32_e32 v1, v254, v1, vcc
	v_lshlrev_b32_e32 v50, 2, v1
	v_xor_b32_e32 v1, 4, v254
	v_cmp_lt_i32_e32 vcc, v1, v0
	s_ashr_i32 s27, s26, 31
	s_lshl_b32 s6, s33, 4
	v_cndmask_b32_e32 v1, v254, v1, vcc
	v_lshlrev_b32_e32 v51, 2, v1
	v_xor_b32_e32 v1, 2, v254
	v_cmp_lt_i32_e32 vcc, v1, v0
	v_readlane_b32 s37, v255, 4
	v_readlane_b32 s38, v255, 5
	v_cndmask_b32_e32 v1, v254, v1, vcc
	v_lshlrev_b32_e32 v52, 2, v1
	v_xor_b32_e32 v1, 1, v254
	v_cmp_lt_i32_e32 vcc, v1, v0
	v_lshl_add_u64 v[24:25], s[36:37], 0, v[22:23]
	v_lshlrev_b64 v[18:19], 1, v[16:17]
	v_cndmask_b32_e32 v0, v254, v1, vcc
	v_lshlrev_b32_e32 v53, 2, v0
	v_lshl_add_u64 v[0:1], s[44:45], 0, v[22:23]
	v_lshl_add_u64 v[28:29], v[0:1], 0, s[0:1]
	s_lshl_b64 s[0:1], s[26:27], 13
	s_add_u32 s10, s62, s0
	s_addc_u32 s11, s63, s1
	s_add_i32 s0, s26, s82
	s_ashr_i32 s7, s6, 31
	s_ashr_i32 s1, s0, 31
	s_lshl_b64 s[12:13], s[6:7], 13
	s_lshl_b64 s[4:5], s[0:1], 11
	s_add_u32 s14, s60, s4
	s_addc_u32 s15, s61, s5
	s_lshl_b64 s[16:17], s[6:7], 11
	s_lshl_b64 s[4:5], s[26:27], 12
	s_add_u32 s18, s36, s4
	s_addc_u32 s19, s37, s5
	s_lshl_b64 s[20:21], s[6:7], 12
	s_lshl_b64 s[0:1], s[0:1], 12
	s_add_u32 s24, s30, s0
	s_addc_u32 s25, s31, s1
	s_add_u32 s36, s30, s4
	s_addc_u32 s37, s31, s5
	s_lshl_b64 s[0:1], s[26:27], 11
	v_readlane_b32 s39, v255, 6
	v_readlane_b32 s40, v255, 7
	v_readlane_b32 s41, v255, 8
	v_readlane_b32 s42, v255, 9
	v_readlane_b32 s43, v255, 10
	v_readlane_b32 s46, v255, 13
	v_readlane_b32 s47, v255, 14
	s_add_u32 s38, s60, s0
	v_lshl_add_u64 v[20:21], s[62:63], 0, v[18:19]
	v_lshl_add_u64 v[26:27], s[46:47], 0, v[22:23]
	s_addc_u32 s39, s61, s1
	s_mov_b64 s[40:41], 0x2000
	s_movk_i32 s0, 0x2000
	v_mov_b32_e32 v54, 0x358637bd
	s_mov_b32 s1, 0x800000
	s_mov_b64 s[42:43], 0xc000
	s_mov_b64 s[44:45], 0xd000
	s_mov_b32 s4, 0xd000
	s_mov_b32 s5, s26
	v_readlane_b32 s48, v255, 15
	v_readlane_b32 s49, v255, 16
	v_readlane_b32 s50, v255, 17
	v_readlane_b32 s51, v255, 18
	s_branch .LBB0_311

.LBB0_330:
	ds_read_b128 v[156:159], v151
	ds_read_b128 v[160:163], v151 offset:1024
	ds_read_b128 v[164:167], v151 offset:2048
	ds_read_b128 v[168:171], v151 offset:3072
	ds_read_b128 v[172:175], v152
	ds_read_b128 v[176:179], v152 offset:1024
	ds_read_b128 v[180:183], v152 offset:2048
	ds_read_b128 v[184:187], v152 offset:3072
	s_add_u32 s38, s10, 0xfffc0080
	s_addc_u32 s39, s11, -1
	s_cmp_eq_u32 s65, 12
	s_cselect_b32 s41, s19, s39
	s_cselect_b32 s40, s51, s38
	s_cselect_b32 s39, s17, s64
	s_cselect_b32 s38, s54, s55
	v_lshl_add_u64 v[222:223], s[10:11], 0, v[136:137]
	s_add_i32 m0, s0, 0xc000
	ds_read_b128 v[188:191], v153
	ds_read_b128 v[192:195], v153 offset:1024
	ds_read_b128 v[196:199], v153 offset:2048
	ds_read_b128 v[200:203], v153 offset:3072
	ds_read_b128 v[204:207], v153 offset:4096
	ds_read_b128 v[208:211], v153 offset:5120
	ds_read_b128 v[212:215], v153 offset:6144
	ds_read_b128 v[218:221], v153 offset:7168
	global_load_lds_dwordx4 v[222:223], off
	v_lshl_add_u64 v[222:223], s[10:11], 0, v[138:139]
	s_add_i32 m0, s0, 0xe000
	s_nop 0
	global_load_lds_dwordx4 v[222:223], off
	s_waitcnt vmcnt(8)
	s_waitcnt lgkmcnt(0)
	s_barrier
	s_waitcnt lgkmcnt(0)
	v_mfma_f32_16x16x32_bf16 v[124:127], v[156:159], v[188:191], v[124:127]
	v_mfma_f32_16x16x32_bf16 v[120:123], v[164:167], v[188:191], v[120:123]
	v_mfma_f32_16x16x32_bf16 v[108:111], v[156:159], v[196:199], v[108:111]
	v_mfma_f32_16x16x32_bf16 v[104:107], v[164:167], v[196:199], v[104:107]
	v_mfma_f32_16x16x32_bf16 v[96:99], v[156:159], v[204:207], v[96:99]
	v_mfma_f32_16x16x32_bf16 v[88:91], v[164:167], v[204:207], v[88:91]
	v_mfma_f32_16x16x32_bf16 v[80:83], v[156:159], v[212:215], v[80:83]
	v_mfma_f32_16x16x32_bf16 v[72:75], v[164:167], v[212:215], v[72:75]
	v_mfma_f32_16x16x32_bf16 v[124:127], v[160:163], v[192:195], v[124:127]
	v_mfma_f32_16x16x32_bf16 v[120:123], v[168:171], v[192:195], v[120:123]
	v_mfma_f32_16x16x32_bf16 v[108:111], v[160:163], v[200:203], v[108:111]
	v_mfma_f32_16x16x32_bf16 v[104:107], v[168:171], v[200:203], v[104:107]
	v_mfma_f32_16x16x32_bf16 v[96:99], v[160:163], v[208:211], v[96:99]
	v_mfma_f32_16x16x32_bf16 v[88:91], v[168:171], v[208:211], v[88:91]
	v_mfma_f32_16x16x32_bf16 v[80:83], v[160:163], v[218:221], v[80:83]
	v_mfma_f32_16x16x32_bf16 v[72:75], v[168:171], v[218:221], v[72:75]
	v_mfma_f32_16x16x32_bf16 v[116:119], v[172:175], v[188:191], v[116:119]
	v_mfma_f32_16x16x32_bf16 v[112:115], v[180:183], v[188:191], v[112:115]
	v_mfma_f32_16x16x32_bf16 v[100:103], v[172:175], v[196:199], v[100:103]
	v_mfma_f32_16x16x32_bf16 v[92:95], v[180:183], v[196:199], v[92:95]
	v_mfma_f32_16x16x32_bf16 v[84:87], v[172:175], v[204:207], v[84:87]
	v_mfma_f32_16x16x32_bf16 v[76:79], v[180:183], v[204:207], v[76:79]
	v_mfma_f32_16x16x32_bf16 v[68:71], v[172:175], v[212:215], v[68:71]
	v_mfma_f32_16x16x32_bf16 v[64:67], v[180:183], v[212:215], v[64:67]
	v_mfma_f32_16x16x32_bf16 v[116:119], v[176:179], v[192:195], v[116:119]
	v_mfma_f32_16x16x32_bf16 v[112:115], v[184:187], v[192:195], v[112:115]
	v_mfma_f32_16x16x32_bf16 v[100:103], v[176:179], v[200:203], v[100:103]
	v_mfma_f32_16x16x32_bf16 v[92:95], v[184:187], v[200:203], v[92:95]
	v_mfma_f32_16x16x32_bf16 v[84:87], v[176:179], v[208:211], v[84:87]
	v_mfma_f32_16x16x32_bf16 v[76:79], v[184:187], v[208:211], v[76:79]
	v_mfma_f32_16x16x32_bf16 v[68:71], v[176:179], v[218:221], v[68:71]
	v_mfma_f32_16x16x32_bf16 v[64:67], v[184:187], v[218:221], v[64:67]
	s_barrier
	s_add_i32 s67, s46, s3
	v_lshl_add_u64 v[222:223], s[38:39], 0, v[132:133]
	s_mov_b32 m0, s67
	ds_read_b128 v[188:191], v153 offset:16384
	ds_read_b128 v[192:195], v153 offset:17408
	ds_read_b128 v[196:199], v153 offset:18432
	ds_read_b128 v[200:203], v153 offset:19456
	ds_read_b128 v[204:207], v153 offset:20480
	ds_read_b128 v[208:211], v153 offset:21504
	ds_read_b128 v[212:215], v153 offset:22528
	ds_read_b128 v[218:221], v153 offset:23552
	global_load_lds_dwordx4 v[222:223], off
	s_add_i32 m0, s67, 0x2000
	s_add_u32 s68, s38, 0x40000
	v_lshl_add_u64 v[224:225], s[38:39], 0, v[128:129]
	s_addc_u32 s69, s39, 0
	s_add_i32 s67, s47, s3
	global_load_lds_dwordx4 v[224:225], off
	v_lshl_add_u64 v[226:227], s[68:69], 0, v[132:133]
	s_mov_b32 m0, s67
	v_lshl_add_u64 v[228:229], s[40:41], 0, v[130:131]
	global_load_lds_dwordx4 v[226:227], off
	v_lshl_add_u64 v[226:227], s[68:69], 0, v[128:129]
	s_add_i32 m0, s67, 0x2000
	s_nop 0
	global_load_lds_dwordx4 v[226:227], off
	v_lshl_add_u64 v[226:227], s[40:41], 0, v[134:135]
	s_mov_b32 m0, s0
	s_nop 0
	global_load_lds_dwordx4 v[226:227], off
	s_mov_b32 m0, s1
	s_nop 0
	global_load_lds_dwordx4 v[228:229], off
	s_waitcnt vmcnt(8)
	s_waitcnt lgkmcnt(0)
	s_barrier
	s_waitcnt lgkmcnt(0)
	v_mfma_f32_16x16x32_bf16 v[60:63], v[156:159], v[188:191], v[60:63]
	v_mfma_f32_16x16x32_bf16 v[56:59], v[164:167], v[188:191], v[56:59]
	v_mfma_f32_16x16x32_bf16 v[52:55], v[156:159], v[196:199], v[52:55]
	v_mfma_f32_16x16x32_bf16 v[44:47], v[164:167], v[196:199], v[44:47]
	v_mfma_f32_16x16x32_bf16 v[36:39], v[156:159], v[204:207], v[36:39]
	v_mfma_f32_16x16x32_bf16 v[28:31], v[164:167], v[204:207], v[28:31]
	v_mfma_f32_16x16x32_bf16 v[20:23], v[156:159], v[212:215], v[20:23]
	v_mfma_f32_16x16x32_bf16 v[12:15], v[164:167], v[212:215], v[12:15]
	v_mfma_f32_16x16x32_bf16 v[60:63], v[160:163], v[192:195], v[60:63]
	v_mfma_f32_16x16x32_bf16 v[56:59], v[168:171], v[192:195], v[56:59]
	v_mfma_f32_16x16x32_bf16 v[52:55], v[160:163], v[200:203], v[52:55]
	v_mfma_f32_16x16x32_bf16 v[44:47], v[168:171], v[200:203], v[44:47]
	v_mfma_f32_16x16x32_bf16 v[36:39], v[160:163], v[208:211], v[36:39]
	v_mfma_f32_16x16x32_bf16 v[28:31], v[168:171], v[208:211], v[28:31]
	v_mfma_f32_16x16x32_bf16 v[20:23], v[160:163], v[218:221], v[20:23]
	v_mfma_f32_16x16x32_bf16 v[12:15], v[168:171], v[218:221], v[12:15]
	v_mfma_f32_16x16x32_bf16 v[48:51], v[172:175], v[188:191], v[48:51]
	v_mfma_f32_16x16x32_bf16 v[40:43], v[180:183], v[188:191], v[40:43]
	v_mfma_f32_16x16x32_bf16 v[32:35], v[172:175], v[196:199], v[32:35]
	v_mfma_f32_16x16x32_bf16 v[24:27], v[180:183], v[196:199], v[24:27]
	v_mfma_f32_16x16x32_bf16 v[16:19], v[172:175], v[204:207], v[16:19]
	v_mfma_f32_16x16x32_bf16 v[8:11], v[180:183], v[204:207], v[8:11]
	v_mfma_f32_16x16x32_bf16 v[4:7], v[172:175], v[212:215], v[4:7]
	v_mfma_f32_16x16x32_bf16 v[0:3], v[180:183], v[212:215], v[0:3]
	v_mfma_f32_16x16x32_bf16 v[48:51], v[176:179], v[192:195], v[48:51]
	v_mfma_f32_16x16x32_bf16 v[40:43], v[184:187], v[192:195], v[40:43]
	v_mfma_f32_16x16x32_bf16 v[32:35], v[176:179], v[200:203], v[32:35]
	v_mfma_f32_16x16x32_bf16 v[24:27], v[184:187], v[200:203], v[24:27]
	v_mfma_f32_16x16x32_bf16 v[16:19], v[176:179], v[208:211], v[16:19]
	v_mfma_f32_16x16x32_bf16 v[8:11], v[184:187], v[208:211], v[8:11]
	v_mfma_f32_16x16x32_bf16 v[4:7], v[176:179], v[218:221], v[4:7]
	v_mfma_f32_16x16x32_bf16 v[0:3], v[184:187], v[218:221], v[0:3]
	s_barrier
	s_add_i32 s67, 0, 0x18000
	v_add_u32_e32 v168, s67, v145
	v_add_u32_e32 v184, s72, v145
	ds_read_b128 v[156:159], v168
	ds_read_b128 v[160:163], v168 offset:1024
	ds_read_b128 v[164:167], v168 offset:2048
	ds_read_b128 v[168:171], v168 offset:3072
	ds_read_b128 v[172:175], v184
	ds_read_b128 v[176:179], v184 offset:1024
	ds_read_b128 v[180:183], v184 offset:2048
	ds_read_b128 v[184:187], v184 offset:3072
	s_add_u32 s40, s40, 0x40000
	s_addc_u32 s41, s41, 0
	s_mov_b32 m0, s27
	v_lshl_add_u64 v[230:231], s[40:41], 0, v[134:135]
	ds_read_b128 v[188:191], v153 offset:32768
	ds_read_b128 v[192:195], v153 offset:33792
	ds_read_b128 v[196:199], v153 offset:34816
	ds_read_b128 v[200:203], v153 offset:35840
	ds_read_b128 v[204:207], v153 offset:36864
	ds_read_b128 v[208:211], v153 offset:37888
	ds_read_b128 v[212:215], v153 offset:38912
	ds_read_b128 v[218:221], v153 offset:39936
	global_load_lds_dwordx4 v[230:231], off
	v_lshl_add_u64 v[230:231], s[40:41], 0, v[130:131]
	s_mov_b32 m0, s37
	s_nop 0
	global_load_lds_dwordx4 v[230:231], off
	s_waitcnt vmcnt(8)
	s_waitcnt lgkmcnt(0)
	s_barrier
	s_waitcnt lgkmcnt(0)
	v_mfma_f32_16x16x32_bf16 v[124:127], v[156:159], v[188:191], v[124:127]
	v_mfma_f32_16x16x32_bf16 v[120:123], v[164:167], v[188:191], v[120:123]
	v_mfma_f32_16x16x32_bf16 v[108:111], v[156:159], v[196:199], v[108:111]
	v_mfma_f32_16x16x32_bf16 v[104:107], v[164:167], v[196:199], v[104:107]
	v_mfma_f32_16x16x32_bf16 v[96:99], v[156:159], v[204:207], v[96:99]
	v_mfma_f32_16x16x32_bf16 v[88:91], v[164:167], v[204:207], v[88:91]
	v_mfma_f32_16x16x32_bf16 v[80:83], v[156:159], v[212:215], v[80:83]
	v_mfma_f32_16x16x32_bf16 v[72:75], v[164:167], v[212:215], v[72:75]
	v_mfma_f32_16x16x32_bf16 v[124:127], v[160:163], v[192:195], v[124:127]
	v_mfma_f32_16x16x32_bf16 v[120:123], v[168:171], v[192:195], v[120:123]
	v_mfma_f32_16x16x32_bf16 v[108:111], v[160:163], v[200:203], v[108:111]
	v_mfma_f32_16x16x32_bf16 v[104:107], v[168:171], v[200:203], v[104:107]
	v_mfma_f32_16x16x32_bf16 v[96:99], v[160:163], v[208:211], v[96:99]
	v_mfma_f32_16x16x32_bf16 v[88:91], v[168:171], v[208:211], v[88:91]
	v_mfma_f32_16x16x32_bf16 v[80:83], v[160:163], v[218:221], v[80:83]
	v_mfma_f32_16x16x32_bf16 v[72:75], v[168:171], v[218:221], v[72:75]
	v_mfma_f32_16x16x32_bf16 v[116:119], v[172:175], v[188:191], v[116:119]
	v_mfma_f32_16x16x32_bf16 v[112:115], v[180:183], v[188:191], v[112:115]
	v_mfma_f32_16x16x32_bf16 v[100:103], v[172:175], v[196:199], v[100:103]
	v_mfma_f32_16x16x32_bf16 v[92:95], v[180:183], v[196:199], v[92:95]
	v_mfma_f32_16x16x32_bf16 v[84:87], v[172:175], v[204:207], v[84:87]
	v_mfma_f32_16x16x32_bf16 v[76:79], v[180:183], v[204:207], v[76:79]
	v_mfma_f32_16x16x32_bf16 v[68:71], v[172:175], v[212:215], v[68:71]
	v_mfma_f32_16x16x32_bf16 v[64:67], v[180:183], v[212:215], v[64:67]
	v_mfma_f32_16x16x32_bf16 v[116:119], v[176:179], v[192:195], v[116:119]
	v_mfma_f32_16x16x32_bf16 v[112:115], v[184:187], v[192:195], v[112:115]
	v_mfma_f32_16x16x32_bf16 v[100:103], v[176:179], v[200:203], v[100:103]
	v_mfma_f32_16x16x32_bf16 v[92:95], v[184:187], v[200:203], v[92:95]
	v_mfma_f32_16x16x32_bf16 v[84:87], v[176:179], v[208:211], v[84:87]
	v_mfma_f32_16x16x32_bf16 v[76:79], v[184:187], v[208:211], v[76:79]
	v_mfma_f32_16x16x32_bf16 v[68:71], v[176:179], v[218:221], v[68:71]
	v_mfma_f32_16x16x32_bf16 v[64:67], v[184:187], v[218:221], v[64:67]
	s_barrier
	s_add_i32 s40, s67, s3
	v_lshl_add_u64 v[222:223], v[222:223], 0, s[14:15]
	s_mov_b32 m0, s40
	ds_read_b128 v[188:191], v153 offset:49152
	ds_read_b128 v[192:195], v153 offset:50176
	ds_read_b128 v[196:199], v153 offset:51200
	ds_read_b128 v[200:203], v153 offset:52224
	ds_read_b128 v[204:207], v153 offset:53248
	ds_read_b128 v[208:211], v153 offset:54272
	ds_read_b128 v[212:215], v153 offset:55296
	ds_read_b128 v[218:221], v153 offset:56320
	global_load_lds_dwordx4 v[222:223], off
	s_add_i32 m0, s40, 0x2000
	s_add_u32 s38, s38, 0x40080
	v_lshl_add_u64 v[222:223], v[224:225], 0, s[14:15]
	s_addc_u32 s39, s39, 0
	s_add_i32 s40, s72, s3
	global_load_lds_dwordx4 v[222:223], off
	v_lshl_add_u64 v[222:223], s[38:39], 0, v[132:133]
	s_mov_b32 m0, s40
	s_nop 0
	global_load_lds_dwordx4 v[222:223], off
	v_lshl_add_u64 v[222:223], s[38:39], 0, v[128:129]
	s_add_i32 m0, s40, 0x2000
	s_nop 0
	global_load_lds_dwordx4 v[222:223], off
	v_lshl_add_u64 v[222:223], v[226:227], 0, s[14:15]
	s_mov_b32 m0, s43
	s_nop 0
	global_load_lds_dwordx4 v[222:223], off
	v_lshl_add_u64 v[222:223], v[228:229], 0, s[14:15]
	s_mov_b32 m0, s44
	s_nop 0
	global_load_lds_dwordx4 v[222:223], off
	s_waitcnt vmcnt(8)
	s_waitcnt lgkmcnt(0)
	s_barrier
	s_waitcnt lgkmcnt(0)
	v_mfma_f32_16x16x32_bf16 v[60:63], v[156:159], v[188:191], v[60:63]
	v_mfma_f32_16x16x32_bf16 v[56:59], v[164:167], v[188:191], v[56:59]
	v_mfma_f32_16x16x32_bf16 v[52:55], v[156:159], v[196:199], v[52:55]
	v_mfma_f32_16x16x32_bf16 v[44:47], v[164:167], v[196:199], v[44:47]
	v_mfma_f32_16x16x32_bf16 v[36:39], v[156:159], v[204:207], v[36:39]
	v_mfma_f32_16x16x32_bf16 v[28:31], v[164:167], v[204:207], v[28:31]
	v_mfma_f32_16x16x32_bf16 v[20:23], v[156:159], v[212:215], v[20:23]
	v_mfma_f32_16x16x32_bf16 v[12:15], v[164:167], v[212:215], v[12:15]
	v_mfma_f32_16x16x32_bf16 v[60:63], v[160:163], v[192:195], v[60:63]
	v_mfma_f32_16x16x32_bf16 v[56:59], v[168:171], v[192:195], v[56:59]
	v_mfma_f32_16x16x32_bf16 v[52:55], v[160:163], v[200:203], v[52:55]
	v_mfma_f32_16x16x32_bf16 v[44:47], v[168:171], v[200:203], v[44:47]
	v_mfma_f32_16x16x32_bf16 v[36:39], v[160:163], v[208:211], v[36:39]
	v_mfma_f32_16x16x32_bf16 v[28:31], v[168:171], v[208:211], v[28:31]
	v_mfma_f32_16x16x32_bf16 v[20:23], v[160:163], v[218:221], v[20:23]
	v_mfma_f32_16x16x32_bf16 v[12:15], v[168:171], v[218:221], v[12:15]
	v_mfma_f32_16x16x32_bf16 v[48:51], v[172:175], v[188:191], v[48:51]
	v_mfma_f32_16x16x32_bf16 v[40:43], v[180:183], v[188:191], v[40:43]
	v_mfma_f32_16x16x32_bf16 v[32:35], v[172:175], v[196:199], v[32:35]
	v_mfma_f32_16x16x32_bf16 v[24:27], v[180:183], v[196:199], v[24:27]
	v_mfma_f32_16x16x32_bf16 v[16:19], v[172:175], v[204:207], v[16:19]
	v_mfma_f32_16x16x32_bf16 v[8:11], v[180:183], v[204:207], v[8:11]
	v_mfma_f32_16x16x32_bf16 v[4:7], v[172:175], v[212:215], v[4:7]
	v_mfma_f32_16x16x32_bf16 v[0:3], v[180:183], v[212:215], v[0:3]
	v_mfma_f32_16x16x32_bf16 v[48:51], v[176:179], v[192:195], v[48:51]
	v_mfma_f32_16x16x32_bf16 v[40:43], v[184:187], v[192:195], v[40:43]
	v_mfma_f32_16x16x32_bf16 v[32:35], v[176:179], v[200:203], v[32:35]
	v_mfma_f32_16x16x32_bf16 v[24:27], v[184:187], v[200:203], v[24:27]
	v_mfma_f32_16x16x32_bf16 v[16:19], v[176:179], v[208:211], v[16:19]
	v_mfma_f32_16x16x32_bf16 v[8:11], v[184:187], v[208:211], v[8:11]
	v_mfma_f32_16x16x32_bf16 v[4:7], v[176:179], v[218:221], v[4:7]
	v_mfma_f32_16x16x32_bf16 v[0:3], v[184:187], v[218:221], v[0:3]
	s_barrier
	s_add_i32 s65, s65, 2
	s_add_u32 s10, s10, 0x100
	s_addc_u32 s11, s11, 0
	s_add_u32 s55, s55, 0x100
	s_addc_u32 s64, s64, 0
	s_cmp_gt_u32 s65, 13
	s_cbranch_scc0 .LBB0_330
	s_and_b64 vcc, exec, s[28:29]
	s_cbranch_vccz .LBB0_333
	s_barrier

.LBB0_345:
	s_setprio 0
	v_readlane_b32 s0, v255, 1
	s_barrier
	v_mbcnt_lo_u32_b32 v33, -1, 0
	v_mbcnt_hi_u32_b32 v33, -1, v33
	s_cmpk_gt_u32 s2, 0x7ff
	v_add_u32_e32 v0, s0, v33
	v_ashrrev_i32_e32 v32, 5, v0
	v_and_b32_e32 v34, 31, v33
	s_cbranch_scc1 .LBB0_347
	s_lshl_b32 s0, s2, 4
	s_lshl_b32 s1, s2, 6
	s_and_b32 s0, s0, 0x6000
	s_and_b32 s1, s1, 0x1fc0
	s_or_b32 s0, s0, s1
	v_add_u32_e32 v2, s0, v32
	s_movk_i32 s0, 0x3000
	v_mov_b64_e32 v[0:1], s[62:63]
	v_mad_i64_i32 v[0:1], s[0:1], v2, s0, v[0:1]
	s_lshl_b32 s0, s2, 2
	s_and_b32 s0, s0, 0x600
	s_mov_b32 s1, 0
	v_lshl_add_u64 v[0:1], v[0:1], 0, s[0:1]
	v_lshlrev_b32_e32 v2, 4, v34
	v_mov_b32_e32 v3, 0
	v_lshl_add_u64 v[20:21], v[0:1], 0, v[2:3]
	s_mov_b32 s0, 0x30000
	v_add_co_u32_e32 v12, vcc, s0, v20
	s_mov_b32 s0, 0x60000
	s_nop 0
	v_addc_co_u32_e32 v13, vcc, 0, v21, vcc
	v_add_co_u32_e32 v22, vcc, s0, v20
	s_mov_b32 s0, 0x90000
	s_nop 0
	v_addc_co_u32_e32 v23, vcc, 0, v21, vcc
	v_add_co_u32_e32 v36, vcc, s0, v20
	global_load_dwordx4 v[0:3], v[20:21], off
	global_load_dwordx4 v[4:7], v[20:21], off offset:2048
	v_addc_co_u32_e32 v37, vcc, 0, v21, vcc
	global_load_dwordx4 v[16:19], v[12:13], off
	global_load_dwordx4 v[8:11], v[12:13], off offset:2048
	global_load_dwordx4 v[24:27], v[22:23], off
	s_nop 0
	global_load_dwordx4 v[12:15], v[22:23], off offset:2048
	global_load_dwordx4 v[28:31], v[36:37], off
	s_nop 0
	global_load_dwordx4 v[20:23], v[36:37], off offset:2048
	s_branch .LBB0_348

.LBB0_386:
	ds_read_b128 v[0:3], v139
	ds_read_b128 v[4:7], v139 offset:1024
	ds_read_b128 v[8:11], v139 offset:2048
	ds_read_b128 v[12:15], v139 offset:3072
	ds_read_b128 v[16:19], v144
	ds_read_b128 v[20:23], v144 offset:1024
	ds_read_b128 v[24:27], v144 offset:2048
	ds_read_b128 v[28:31], v144 offset:3072
	s_ashr_i32 s36, s55, 5
	s_and_b32 s81, s55, 1
	s_ashr_i32 s37, s36, 31
	s_lshl_b32 s40, s81, 17
	s_lshl_b64 s[36:37], s[36:37], 18
	s_add_u32 s40, s0, s40
	s_addc_u32 s41, s1, 0
	s_add_u32 s36, s40, s36
	s_addc_u32 s37, s41, s37
	s_and_b64 s[40:41], s[24:25], exec
	s_cselect_b32 s41, s37, s43
	s_cselect_b32 s40, s36, s42
	s_add_u32 s84, s38, 0x180080
	s_addc_u32 s85, s39, 0
	s_mov_b32 m0, s56
	v_lshl_add_u64 v[64:65], s[84:85], 0, v[134:135]
	ds_read_b128 v[32:35], v145
	ds_read_b128 v[36:39], v145 offset:1024
	ds_read_b128 v[40:43], v145 offset:2048
	ds_read_b128 v[44:47], v145 offset:3072
	ds_read_b128 v[48:51], v145 offset:4096
	ds_read_b128 v[52:55], v145 offset:5120
	ds_read_b128 v[56:59], v145 offset:6144
	ds_read_b128 v[60:63], v145 offset:7168
	global_load_lds_dwordx4 v[64:65], off
	v_lshl_add_u64 v[64:65], s[84:85], 0, v[130:131]
	s_mov_b32 m0, s57
	s_nop 0
	global_load_lds_dwordx4 v[64:65], off
	s_waitcnt vmcnt(8)
	s_waitcnt lgkmcnt(0)
	s_barrier
	s_waitcnt lgkmcnt(0)
	v_mfma_f32_16x16x32_bf16 v[64:67], v[0:3], v[32:35], 0
	v_mfma_f32_16x16x32_bf16 v[68:71], v[8:11], v[32:35], 0
	v_mfma_f32_16x16x32_bf16 v[72:75], v[0:3], v[40:43], 0
	v_mfma_f32_16x16x32_bf16 v[76:79], v[8:11], v[40:43], 0
	v_mfma_f32_16x16x32_bf16 v[80:83], v[0:3], v[48:51], 0
	v_mfma_f32_16x16x32_bf16 v[84:87], v[8:11], v[48:51], 0
	v_mfma_f32_16x16x32_bf16 v[88:91], v[0:3], v[56:59], 0
	v_mfma_f32_16x16x32_bf16 v[92:95], v[8:11], v[56:59], 0
	v_mfma_f32_16x16x32_bf16 v[64:67], v[4:7], v[36:39], v[64:67]
	v_mfma_f32_16x16x32_bf16 v[68:71], v[12:15], v[36:39], v[68:71]
	v_mfma_f32_16x16x32_bf16 v[72:75], v[4:7], v[44:47], v[72:75]
	v_mfma_f32_16x16x32_bf16 v[76:79], v[12:15], v[44:47], v[76:79]
	v_mfma_f32_16x16x32_bf16 v[80:83], v[4:7], v[52:55], v[80:83]
	v_mfma_f32_16x16x32_bf16 v[84:87], v[12:15], v[52:55], v[84:87]
	v_mfma_f32_16x16x32_bf16 v[88:91], v[4:7], v[60:63], v[88:91]
	v_mfma_f32_16x16x32_bf16 v[92:95], v[12:15], v[60:63], v[92:95]
	v_mfma_f32_16x16x32_bf16 v[96:99], v[16:19], v[32:35], 0
	v_mfma_f32_16x16x32_bf16 v[32:35], v[24:27], v[32:35], 0
	v_mfma_f32_16x16x32_bf16 v[96:99], v[20:23], v[36:39], v[96:99]
	v_mfma_f32_16x16x32_bf16 v[32:35], v[28:31], v[36:39], v[32:35]
	v_mfma_f32_16x16x32_bf16 v[36:39], v[16:19], v[40:43], 0
	v_mfma_f32_16x16x32_bf16 v[40:43], v[24:27], v[40:43], 0
	v_mfma_f32_16x16x32_bf16 v[36:39], v[20:23], v[44:47], v[36:39]
	v_mfma_f32_16x16x32_bf16 v[40:43], v[28:31], v[44:47], v[40:43]
	v_mfma_f32_16x16x32_bf16 v[44:47], v[16:19], v[48:51], 0
	v_mfma_f32_16x16x32_bf16 v[48:51], v[24:27], v[48:51], 0
	v_mfma_f32_16x16x32_bf16 v[44:47], v[20:23], v[52:55], v[44:47]
	v_mfma_f32_16x16x32_bf16 v[48:51], v[28:31], v[52:55], v[48:51]
	v_mfma_f32_16x16x32_bf16 v[52:55], v[16:19], v[56:59], 0
	v_mfma_f32_16x16x32_bf16 v[56:59], v[24:27], v[56:59], 0
	v_mfma_f32_16x16x32_bf16 v[52:55], v[20:23], v[60:63], v[52:55]
	v_mfma_f32_16x16x32_bf16 v[56:59], v[28:31], v[60:63], v[56:59]
	s_barrier
	v_lshl_add_u64 v[142:143], s[42:43], 0, v[132:133]
	s_mov_b32 m0, s64
	v_lshl_add_u64 v[150:151], v[142:143], 0, s[18:19]
	v_lshl_add_u64 v[214:215], s[42:43], 0, v[128:129]
	s_add_u32 s84, s42, 0x10100
	ds_read_b128 v[60:63], v145 offset:16384
	ds_read_b128 v[100:103], v145 offset:17408
	ds_read_b128 v[104:107], v145 offset:18432
	ds_read_b128 v[108:111], v145 offset:19456
	ds_read_b128 v[112:115], v145 offset:20480
	ds_read_b128 v[116:119], v145 offset:21504
	ds_read_b128 v[120:123], v145 offset:22528
	ds_read_b128 v[124:127], v145 offset:23552
	global_load_lds_dwordx4 v[150:151], off
	v_lshl_add_u64 v[150:151], v[214:215], 0, s[18:19]
	s_mov_b32 m0, s73
	s_addc_u32 s85, s43, 0
	global_load_lds_dwordx4 v[150:151], off
	v_lshl_add_u64 v[150:151], s[84:85], 0, v[132:133]
	s_mov_b32 m0, s74
	v_lshl_add_u64 v[218:219], s[38:39], 0, v[134:135]
	global_load_lds_dwordx4 v[150:151], off
	v_lshl_add_u64 v[150:151], s[84:85], 0, v[128:129]
	s_mov_b32 m0, s75
	v_lshl_add_u64 v[220:221], s[38:39], 0, v[130:131]
	global_load_lds_dwordx4 v[150:151], off
	v_lshl_add_u64 v[150:151], v[218:219], 0, s[18:19]
	s_mov_b32 m0, s46
	s_nop 0
	global_load_lds_dwordx4 v[150:151], off
	v_lshl_add_u64 v[150:151], v[220:221], 0, s[18:19]
	s_mov_b32 m0, s47
	s_nop 0
	global_load_lds_dwordx4 v[150:151], off
	s_waitcnt vmcnt(8)
	s_waitcnt lgkmcnt(0)
	s_barrier
	s_waitcnt lgkmcnt(0)
	v_mfma_f32_16x16x32_bf16 v[150:153], v[0:3], v[60:63], 0
	v_mfma_f32_16x16x32_bf16 v[158:161], v[0:3], v[104:107], 0
	v_mfma_f32_16x16x32_bf16 v[166:169], v[0:3], v[112:115], 0
	v_mfma_f32_16x16x32_bf16 v[0:3], v[0:3], v[120:123], 0
	v_mfma_f32_16x16x32_bf16 v[150:153], v[4:7], v[100:103], v[150:153]
	v_mfma_f32_16x16x32_bf16 v[158:161], v[4:7], v[108:111], v[158:161]
	v_mfma_f32_16x16x32_bf16 v[166:169], v[4:7], v[116:119], v[166:169]
	v_mfma_f32_16x16x32_bf16 v[0:3], v[4:7], v[124:127], v[0:3]
	v_mfma_f32_16x16x32_bf16 v[4:7], v[8:11], v[120:123], 0
	v_mfma_f32_16x16x32_bf16 v[154:157], v[8:11], v[60:63], 0
	v_mfma_f32_16x16x32_bf16 v[162:165], v[8:11], v[104:107], 0
	v_mfma_f32_16x16x32_bf16 v[170:173], v[8:11], v[112:115], 0
	v_mfma_f32_16x16x32_bf16 v[4:7], v[12:15], v[124:127], v[4:7]
	v_mfma_f32_16x16x32_bf16 v[154:157], v[12:15], v[100:103], v[154:157]
	v_mfma_f32_16x16x32_bf16 v[162:165], v[12:15], v[108:111], v[162:165]
	v_mfma_f32_16x16x32_bf16 v[170:173], v[12:15], v[116:119], v[170:173]
	v_mfma_f32_16x16x32_bf16 v[8:11], v[16:19], v[60:63], 0
	v_mfma_f32_16x16x32_bf16 v[12:15], v[24:27], v[60:63], 0
	v_mfma_f32_16x16x32_bf16 v[8:11], v[20:23], v[100:103], v[8:11]
	v_mfma_f32_16x16x32_bf16 v[12:15], v[28:31], v[100:103], v[12:15]
	v_mfma_f32_16x16x32_bf16 v[60:63], v[16:19], v[104:107], 0
	v_mfma_f32_16x16x32_bf16 v[100:103], v[24:27], v[104:107], 0
	v_mfma_f32_16x16x32_bf16 v[104:107], v[16:19], v[112:115], 0
	v_mfma_f32_16x16x32_bf16 v[16:19], v[16:19], v[120:123], 0
	v_mfma_f32_16x16x32_bf16 v[60:63], v[20:23], v[108:111], v[60:63]
	v_mfma_f32_16x16x32_bf16 v[100:103], v[28:31], v[108:111], v[100:103]
	v_mfma_f32_16x16x32_bf16 v[104:107], v[20:23], v[116:119], v[104:107]
	v_mfma_f32_16x16x32_bf16 v[108:111], v[24:27], v[112:115], 0
	v_mfma_f32_16x16x32_bf16 v[16:19], v[20:23], v[124:127], v[16:19]
	v_mfma_f32_16x16x32_bf16 v[20:23], v[24:27], v[120:123], 0
	v_mfma_f32_16x16x32_bf16 v[108:111], v[28:31], v[116:119], v[108:111]
	v_mfma_f32_16x16x32_bf16 v[20:23], v[28:31], v[124:127], v[20:23]
	s_barrier
	ds_read_b128 v[24:27], v146
	ds_read_b128 v[28:31], v146 offset:1024
	ds_read_b128 v[112:115], v146 offset:2048
	ds_read_b128 v[116:119], v146 offset:3072
	ds_read_b128 v[120:123], v147
	ds_read_b128 v[124:127], v147 offset:1024
	ds_read_b128 v[174:177], v147 offset:2048
	ds_read_b128 v[178:181], v147 offset:3072
	s_add_u32 s84, s38, 0x180100
	s_addc_u32 s85, s39, 0
	s_mov_b32 m0, s48
	v_lshl_add_u64 v[222:223], s[84:85], 0, v[134:135]
	ds_read_b128 v[182:185], v145 offset:32768
	ds_read_b128 v[186:189], v145 offset:33792
	ds_read_b128 v[190:193], v145 offset:34816
	ds_read_b128 v[194:197], v145 offset:35840
	ds_read_b128 v[198:201], v145 offset:36864
	ds_read_b128 v[202:205], v145 offset:37888
	ds_read_b128 v[206:209], v145 offset:38912
	ds_read_b128 v[210:213], v145 offset:39936
	global_load_lds_dwordx4 v[222:223], off
	v_lshl_add_u64 v[222:223], s[84:85], 0, v[130:131]
	s_mov_b32 m0, s49
	s_nop 0
	global_load_lds_dwordx4 v[222:223], off
	s_waitcnt vmcnt(8)
	s_waitcnt lgkmcnt(0)
	s_barrier
	s_waitcnt lgkmcnt(0)
	v_mfma_f32_16x16x32_bf16 v[64:67], v[24:27], v[182:185], v[64:67]
	v_mfma_f32_16x16x32_bf16 v[68:71], v[112:115], v[182:185], v[68:71]
	v_mfma_f32_16x16x32_bf16 v[72:75], v[24:27], v[190:193], v[72:75]
	v_mfma_f32_16x16x32_bf16 v[76:79], v[112:115], v[190:193], v[76:79]
	v_mfma_f32_16x16x32_bf16 v[80:83], v[24:27], v[198:201], v[80:83]
	v_mfma_f32_16x16x32_bf16 v[84:87], v[112:115], v[198:201], v[84:87]
	v_mfma_f32_16x16x32_bf16 v[88:91], v[24:27], v[206:209], v[88:91]
	v_mfma_f32_16x16x32_bf16 v[92:95], v[112:115], v[206:209], v[92:95]
	v_mfma_f32_16x16x32_bf16 v[64:67], v[28:31], v[186:189], v[64:67]
	v_mfma_f32_16x16x32_bf16 v[68:71], v[116:119], v[186:189], v[68:71]
	v_mfma_f32_16x16x32_bf16 v[72:75], v[28:31], v[194:197], v[72:75]
	v_mfma_f32_16x16x32_bf16 v[76:79], v[116:119], v[194:197], v[76:79]
	v_mfma_f32_16x16x32_bf16 v[80:83], v[28:31], v[202:205], v[80:83]
	v_mfma_f32_16x16x32_bf16 v[84:87], v[116:119], v[202:205], v[84:87]
	v_mfma_f32_16x16x32_bf16 v[88:91], v[28:31], v[210:213], v[88:91]
	v_mfma_f32_16x16x32_bf16 v[92:95], v[116:119], v[210:213], v[92:95]
	v_mfma_f32_16x16x32_bf16 v[96:99], v[120:123], v[182:185], v[96:99]
	v_mfma_f32_16x16x32_bf16 v[32:35], v[174:177], v[182:185], v[32:35]
	v_mfma_f32_16x16x32_bf16 v[36:39], v[120:123], v[190:193], v[36:39]
	v_mfma_f32_16x16x32_bf16 v[40:43], v[174:177], v[190:193], v[40:43]
	v_mfma_f32_16x16x32_bf16 v[44:47], v[120:123], v[198:201], v[44:47]
	v_mfma_f32_16x16x32_bf16 v[48:51], v[174:177], v[198:201], v[48:51]
	v_mfma_f32_16x16x32_bf16 v[52:55], v[120:123], v[206:209], v[52:55]
	v_mfma_f32_16x16x32_bf16 v[56:59], v[174:177], v[206:209], v[56:59]
	v_mfma_f32_16x16x32_bf16 v[96:99], v[124:127], v[186:189], v[96:99]
	v_mfma_f32_16x16x32_bf16 v[32:35], v[178:181], v[186:189], v[32:35]
	v_mfma_f32_16x16x32_bf16 v[36:39], v[124:127], v[194:197], v[36:39]
	v_mfma_f32_16x16x32_bf16 v[40:43], v[178:181], v[194:197], v[40:43]
	v_mfma_f32_16x16x32_bf16 v[44:47], v[124:127], v[202:205], v[44:47]
	v_mfma_f32_16x16x32_bf16 v[48:51], v[178:181], v[202:205], v[48:51]
	v_mfma_f32_16x16x32_bf16 v[52:55], v[124:127], v[210:213], v[52:55]
	v_mfma_f32_16x16x32_bf16 v[56:59], v[178:181], v[210:213], v[56:59]
	s_barrier
	s_mov_b32 m0, s76
	v_lshl_add_u64 v[142:143], v[142:143], 0, s[20:21]
	s_add_u32 s42, s42, 0x10180
	ds_read_b128 v[182:185], v145 offset:49152
	ds_read_b128 v[186:189], v145 offset:50176
	ds_read_b128 v[190:193], v145 offset:51200
	ds_read_b128 v[194:197], v145 offset:52224
	ds_read_b128 v[198:201], v145 offset:53248
	ds_read_b128 v[202:205], v145 offset:54272
	ds_read_b128 v[206:209], v145 offset:55296
	ds_read_b128 v[210:213], v145 offset:56320
	global_load_lds_dwordx4 v[142:143], off
	v_lshl_add_u64 v[142:143], v[214:215], 0, s[20:21]
	s_mov_b32 m0, s77
	s_addc_u32 s43, s43, 0
	global_load_lds_dwordx4 v[142:143], off
	v_lshl_add_u64 v[142:143], s[42:43], 0, v[132:133]
	s_mov_b32 m0, s78
	s_nop 0
	global_load_lds_dwordx4 v[142:143], off
	v_lshl_add_u64 v[142:143], s[42:43], 0, v[128:129]
	s_mov_b32 m0, s79
	s_nop 0
	global_load_lds_dwordx4 v[142:143], off
	v_lshl_add_u64 v[142:143], v[218:219], 0, s[20:21]
	s_mov_b32 m0, s51
	s_nop 0
	global_load_lds_dwordx4 v[142:143], off
	v_lshl_add_u64 v[142:143], v[220:221], 0, s[20:21]
	s_mov_b32 m0, s54
	s_nop 0
	global_load_lds_dwordx4 v[142:143], off
	s_waitcnt vmcnt(8)
	s_waitcnt lgkmcnt(0)
	s_barrier
	s_waitcnt lgkmcnt(0)
	v_mfma_f32_16x16x32_bf16 v[0:3], v[24:27], v[206:209], v[0:3]
	v_mfma_f32_16x16x32_bf16 v[4:7], v[112:115], v[206:209], v[4:7]
	v_mfma_f32_16x16x32_bf16 v[150:153], v[24:27], v[182:185], v[150:153]
	v_mfma_f32_16x16x32_bf16 v[154:157], v[112:115], v[182:185], v[154:157]
	v_mfma_f32_16x16x32_bf16 v[158:161], v[24:27], v[190:193], v[158:161]
	v_mfma_f32_16x16x32_bf16 v[162:165], v[112:115], v[190:193], v[162:165]
	v_mfma_f32_16x16x32_bf16 v[166:169], v[24:27], v[198:201], v[166:169]
	v_mfma_f32_16x16x32_bf16 v[170:173], v[112:115], v[198:201], v[170:173]
	v_mfma_f32_16x16x32_bf16 v[0:3], v[28:31], v[210:213], v[0:3]
	v_mfma_f32_16x16x32_bf16 v[4:7], v[116:119], v[210:213], v[4:7]
	v_mfma_f32_16x16x32_bf16 v[150:153], v[28:31], v[186:189], v[150:153]
	v_mfma_f32_16x16x32_bf16 v[154:157], v[116:119], v[186:189], v[154:157]
	v_mfma_f32_16x16x32_bf16 v[158:161], v[28:31], v[194:197], v[158:161]
	v_mfma_f32_16x16x32_bf16 v[162:165], v[116:119], v[194:197], v[162:165]
	v_mfma_f32_16x16x32_bf16 v[166:169], v[28:31], v[202:205], v[166:169]
	v_mfma_f32_16x16x32_bf16 v[170:173], v[116:119], v[202:205], v[170:173]
	v_mfma_f32_16x16x32_bf16 v[8:11], v[120:123], v[182:185], v[8:11]
	v_mfma_f32_16x16x32_bf16 v[12:15], v[174:177], v[182:185], v[12:15]
	v_mfma_f32_16x16x32_bf16 v[24:27], v[120:123], v[190:193], v[60:63]
	v_mfma_f32_16x16x32_bf16 v[28:31], v[174:177], v[190:193], v[100:103]
	v_mfma_f32_16x16x32_bf16 v[60:63], v[120:123], v[198:201], v[104:107]
	v_mfma_f32_16x16x32_bf16 v[100:103], v[174:177], v[198:201], v[108:111]
	v_mfma_f32_16x16x32_bf16 v[16:19], v[120:123], v[206:209], v[16:19]
	v_mfma_f32_16x16x32_bf16 v[20:23], v[174:177], v[206:209], v[20:23]
	v_mfma_f32_16x16x32_bf16 v[8:11], v[124:127], v[186:189], v[8:11]
	v_mfma_f32_16x16x32_bf16 v[12:15], v[178:181], v[186:189], v[12:15]
	v_mfma_f32_16x16x32_bf16 v[24:27], v[124:127], v[194:197], v[24:27]
	v_mfma_f32_16x16x32_bf16 v[28:31], v[178:181], v[194:197], v[28:31]
	v_mfma_f32_16x16x32_bf16 v[60:63], v[124:127], v[202:205], v[60:63]
	v_mfma_f32_16x16x32_bf16 v[100:103], v[178:181], v[202:205], v[100:103]
	v_mfma_f32_16x16x32_bf16 v[16:19], v[124:127], v[210:213], v[16:19]
	v_mfma_f32_16x16x32_bf16 v[20:23], v[178:181], v[210:213], v[20:23]
	s_barrier
	ds_read_b128 v[104:107], v139
	ds_read_b128 v[108:111], v139 offset:1024
	ds_read_b128 v[112:115], v139 offset:2048
	ds_read_b128 v[116:119], v139 offset:3072
	ds_read_b128 v[120:123], v144
	ds_read_b128 v[124:127], v144 offset:1024
	ds_read_b128 v[174:177], v144 offset:2048
	ds_read_b128 v[178:181], v144 offset:3072
	s_add_u32 s38, s38, 0x180180
	s_addc_u32 s39, s39, 0
	s_mov_b32 m0, s56
	v_lshl_add_u64 v[142:143], s[38:39], 0, v[134:135]
	ds_read_b128 v[182:185], v145
	ds_read_b128 v[186:189], v145 offset:1024
	ds_read_b128 v[190:193], v145 offset:2048
	ds_read_b128 v[194:197], v145 offset:3072
	ds_read_b128 v[198:201], v145 offset:4096
	ds_read_b128 v[202:205], v145 offset:5120
	ds_read_b128 v[206:209], v145 offset:6144
	ds_read_b128 v[210:213], v145 offset:7168
	global_load_lds_dwordx4 v[142:143], off
	v_lshl_add_u64 v[142:143], s[38:39], 0, v[130:131]
	s_mov_b32 m0, s57
	s_nop 0
	global_load_lds_dwordx4 v[142:143], off
	s_waitcnt vmcnt(8)
	s_waitcnt lgkmcnt(0)
	s_barrier
	s_waitcnt lgkmcnt(0)
	v_mfma_f32_16x16x32_bf16 v[64:67], v[104:107], v[182:185], v[64:67]
	v_mfma_f32_16x16x32_bf16 v[68:71], v[112:115], v[182:185], v[68:71]
	v_mfma_f32_16x16x32_bf16 v[72:75], v[104:107], v[190:193], v[72:75]
	v_mfma_f32_16x16x32_bf16 v[76:79], v[112:115], v[190:193], v[76:79]
	v_mfma_f32_16x16x32_bf16 v[80:83], v[104:107], v[198:201], v[80:83]
	v_mfma_f32_16x16x32_bf16 v[84:87], v[112:115], v[198:201], v[84:87]
	v_mfma_f32_16x16x32_bf16 v[88:91], v[104:107], v[206:209], v[88:91]
	v_mfma_f32_16x16x32_bf16 v[64:67], v[108:111], v[186:189], v[64:67]
	v_mfma_f32_16x16x32_bf16 v[68:71], v[116:119], v[186:189], v[68:71]
	v_mfma_f32_16x16x32_bf16 v[72:75], v[108:111], v[194:197], v[72:75]
	v_mfma_f32_16x16x32_bf16 v[76:79], v[116:119], v[194:197], v[76:79]
	v_mfma_f32_16x16x32_bf16 v[80:83], v[108:111], v[202:205], v[80:83]
	v_mfma_f32_16x16x32_bf16 v[84:87], v[116:119], v[202:205], v[84:87]
	v_mfma_f32_16x16x32_bf16 v[88:91], v[108:111], v[210:213], v[88:91]
	v_mfma_f32_16x16x32_bf16 v[92:95], v[112:115], v[206:209], v[92:95]
	v_mfma_f32_16x16x32_bf16 v[218:221], v[116:119], v[210:213], v[92:95]
	v_mfma_f32_16x16x32_bf16 v[92:95], v[120:123], v[182:185], v[96:99]
	v_mfma_f32_16x16x32_bf16 v[32:35], v[174:177], v[182:185], v[32:35]
	v_mfma_f32_16x16x32_bf16 v[36:39], v[120:123], v[190:193], v[36:39]
	v_mfma_f32_16x16x32_bf16 v[40:43], v[174:177], v[190:193], v[40:43]
	v_mfma_f32_16x16x32_bf16 v[44:47], v[120:123], v[198:201], v[44:47]
	v_mfma_f32_16x16x32_bf16 v[48:51], v[174:177], v[198:201], v[48:51]
	v_mfma_f32_16x16x32_bf16 v[52:55], v[120:123], v[206:209], v[52:55]
	v_mfma_f32_16x16x32_bf16 v[96:99], v[124:127], v[186:189], v[92:95]
	v_mfma_f32_16x16x32_bf16 v[32:35], v[178:181], v[186:189], v[32:35]
	v_mfma_f32_16x16x32_bf16 v[36:39], v[124:127], v[194:197], v[36:39]
	v_mfma_f32_16x16x32_bf16 v[40:43], v[178:181], v[194:197], v[40:43]
	v_mfma_f32_16x16x32_bf16 v[44:47], v[124:127], v[202:205], v[44:47]
	v_mfma_f32_16x16x32_bf16 v[48:51], v[178:181], v[202:205], v[48:51]
	v_mfma_f32_16x16x32_bf16 v[52:55], v[124:127], v[210:213], v[52:55]
	v_mfma_f32_16x16x32_bf16 v[56:59], v[174:177], v[206:209], v[56:59]
	v_mfma_f32_16x16x32_bf16 v[182:185], v[178:181], v[210:213], v[56:59]
	s_barrier
	s_mov_b32 m0, s64
	v_lshl_add_u64 v[142:143], s[40:41], 0, v[132:133]
	s_add_u32 s38, s40, 0x10000
	s_nop 1
	ds_read_b128 v[56:59], v145 offset:16384
	ds_read_b128 v[92:95], v145 offset:17408
	ds_read_b128 v[186:189], v145 offset:18432
	ds_read_b128 v[190:193], v145 offset:19456
	ds_read_b128 v[194:197], v145 offset:20480
	ds_read_b128 v[198:201], v145 offset:21504
	ds_read_b128 v[202:205], v145 offset:22528
	ds_read_b128 v[206:209], v145 offset:23552
	global_load_lds_dwordx4 v[142:143], off
	v_lshl_add_u64 v[214:215], s[40:41], 0, v[128:129]
	s_mov_b32 m0, s73
	s_addc_u32 s39, s41, 0
	global_load_lds_dwordx4 v[214:215], off
	v_lshl_add_u64 v[210:211], s[38:39], 0, v[132:133]
	s_mov_b32 m0, s74
	v_lshl_add_u64 v[148:149], s[22:23], 0, v[134:135]
	global_load_lds_dwordx4 v[210:211], off
	v_lshl_add_u64 v[210:211], s[38:39], 0, v[128:129]
	s_mov_b32 m0, s75
	v_lshl_add_u64 v[216:217], s[22:23], 0, v[130:131]
	global_load_lds_dwordx4 v[210:211], off
	s_mov_b32 m0, s46
	s_nop 0
	global_load_lds_dwordx4 v[148:149], off
	s_mov_b32 m0, s47
	s_nop 0
	global_load_lds_dwordx4 v[216:217], off
	s_waitcnt vmcnt(8)
	s_waitcnt lgkmcnt(0)
	s_barrier
	s_waitcnt lgkmcnt(0)
	v_mfma_f32_16x16x32_bf16 v[0:3], v[104:107], v[202:205], v[0:3]
	v_mfma_f32_16x16x32_bf16 v[4:7], v[112:115], v[202:205], v[4:7]
	v_mfma_f32_16x16x32_bf16 v[150:153], v[104:107], v[56:59], v[150:153]
	v_mfma_f32_16x16x32_bf16 v[154:157], v[112:115], v[56:59], v[154:157]
	v_mfma_f32_16x16x32_bf16 v[158:161], v[104:107], v[186:189], v[158:161]
	v_mfma_f32_16x16x32_bf16 v[162:165], v[112:115], v[186:189], v[162:165]
	v_mfma_f32_16x16x32_bf16 v[166:169], v[104:107], v[194:197], v[166:169]
	v_mfma_f32_16x16x32_bf16 v[170:173], v[112:115], v[194:197], v[170:173]
	v_mfma_f32_16x16x32_bf16 v[0:3], v[108:111], v[206:209], v[0:3]
	v_mfma_f32_16x16x32_bf16 v[4:7], v[116:119], v[206:209], v[4:7]
	v_mfma_f32_16x16x32_bf16 v[150:153], v[108:111], v[92:95], v[150:153]
	v_mfma_f32_16x16x32_bf16 v[154:157], v[116:119], v[92:95], v[154:157]
	v_mfma_f32_16x16x32_bf16 v[158:161], v[108:111], v[190:193], v[158:161]
	v_mfma_f32_16x16x32_bf16 v[162:165], v[116:119], v[190:193], v[162:165]
	v_mfma_f32_16x16x32_bf16 v[166:169], v[108:111], v[198:201], v[166:169]
	v_mfma_f32_16x16x32_bf16 v[170:173], v[116:119], v[198:201], v[170:173]
	v_mfma_f32_16x16x32_bf16 v[12:15], v[174:177], v[56:59], v[12:15]
	v_mfma_f32_16x16x32_bf16 v[210:213], v[178:181], v[92:95], v[12:15]
	v_mfma_f32_16x16x32_bf16 v[12:15], v[120:123], v[186:189], v[24:27]
	v_mfma_f32_16x16x32_bf16 v[24:27], v[124:127], v[190:193], v[12:15]
	v_mfma_f32_16x16x32_bf16 v[12:15], v[174:177], v[186:189], v[28:31]
	v_mfma_f32_16x16x32_bf16 v[186:189], v[178:181], v[190:193], v[12:15]
	v_mfma_f32_16x16x32_bf16 v[12:15], v[120:123], v[194:197], v[60:63]
	v_mfma_f32_16x16x32_bf16 v[190:193], v[124:127], v[198:201], v[12:15]
	v_mfma_f32_16x16x32_bf16 v[12:15], v[174:177], v[194:197], v[100:103]
	v_mfma_f32_16x16x32_bf16 v[8:11], v[120:123], v[56:59], v[8:11]
	v_mfma_f32_16x16x32_bf16 v[194:197], v[178:181], v[198:201], v[12:15]
	v_mfma_f32_16x16x32_bf16 v[12:15], v[120:123], v[202:205], v[16:19]
	v_mfma_f32_16x16x32_bf16 v[8:11], v[124:127], v[92:95], v[8:11]
	v_mfma_f32_16x16x32_bf16 v[198:201], v[124:127], v[206:209], v[12:15]
	v_mfma_f32_16x16x32_bf16 v[12:15], v[174:177], v[202:205], v[20:23]
	v_mfma_f32_16x16x32_bf16 v[174:177], v[178:181], v[206:209], v[12:15]
	s_barrier
	s_nop 4
	ds_read_b128 v[12:15], v146
	ds_read_b128 v[16:19], v146 offset:1024
	ds_read_b128 v[178:181], v146 offset:2048
	ds_read_b128 v[202:205], v146 offset:3072
	ds_read_b128 v[206:209], v147
	ds_read_b128 v[222:225], v147 offset:1024
	ds_read_b128 v[226:229], v147 offset:2048
	ds_read_b128 v[230:233], v147 offset:3072
	s_add_u32 s38, s22, 0x180000
	s_addc_u32 s39, s23, 0
	s_mov_b32 m0, s48
	v_lshl_add_u64 v[56:57], s[38:39], 0, v[134:135]
	ds_read_b128 v[20:23], v145 offset:32768
	ds_read_b128 v[28:31], v145 offset:33792
	ds_read_b128 v[60:63], v145 offset:34816
	ds_read_b128 v[234:237], v145 offset:35840
	ds_read_b128 v[238:241], v145 offset:36864
	ds_read_b128 v[242:245], v145 offset:37888
	ds_read_b128 v[246:249], v145 offset:38912
	ds_read_b128 v[250:253], v145 offset:39936
	global_load_lds_dwordx4 v[56:57], off
	v_lshl_add_u64 v[56:57], s[38:39], 0, v[130:131]
	s_mov_b32 m0, s49
	s_nop 0
	global_load_lds_dwordx4 v[56:57], off
	s_waitcnt vmcnt(8)
	s_waitcnt lgkmcnt(0)
	s_barrier
	s_waitcnt lgkmcnt(0)
	v_mfma_f32_16x16x32_bf16 v[56:59], v[12:15], v[20:23], v[64:67]
	v_mfma_f32_16x16x32_bf16 v[120:123], v[16:19], v[28:31], v[56:59]
	v_mfma_f32_16x16x32_bf16 v[56:59], v[178:181], v[20:23], v[68:71]
	v_mfma_f32_16x16x32_bf16 v[116:119], v[202:205], v[28:31], v[56:59]
	v_mfma_f32_16x16x32_bf16 v[56:59], v[12:15], v[60:63], v[72:75]
	v_mfma_f32_16x16x32_bf16 v[108:111], v[16:19], v[234:237], v[56:59]
	v_mfma_f32_16x16x32_bf16 v[56:59], v[178:181], v[60:63], v[76:79]
	v_mfma_f32_16x16x32_bf16 v[100:103], v[202:205], v[234:237], v[56:59]
	v_mfma_f32_16x16x32_bf16 v[56:59], v[12:15], v[238:241], v[80:83]
	v_mfma_f32_16x16x32_bf16 v[92:95], v[16:19], v[242:245], v[56:59]
	v_mfma_f32_16x16x32_bf16 v[56:59], v[178:181], v[238:241], v[84:87]
	v_mfma_f32_16x16x32_bf16 v[84:87], v[202:205], v[242:245], v[56:59]
	v_mfma_f32_16x16x32_bf16 v[56:59], v[12:15], v[246:249], v[88:91]
	v_mfma_f32_16x16x32_bf16 v[64:67], v[16:19], v[250:253], v[56:59]
	v_mfma_f32_16x16x32_bf16 v[56:59], v[178:181], v[246:249], v[218:221]
	v_mfma_f32_16x16x32_bf16 v[56:59], v[202:205], v[250:253], v[56:59]
	v_mfma_f32_16x16x32_bf16 v[68:71], v[206:209], v[20:23], v[96:99]
	v_mfma_f32_16x16x32_bf16 v[20:23], v[226:229], v[20:23], v[32:35]
	v_mfma_f32_16x16x32_bf16 v[112:115], v[230:233], v[28:31], v[20:23]
	v_mfma_f32_16x16x32_bf16 v[20:23], v[206:209], v[60:63], v[36:39]
	v_mfma_f32_16x16x32_bf16 v[104:107], v[222:225], v[234:237], v[20:23]
	v_mfma_f32_16x16x32_bf16 v[20:23], v[226:229], v[60:63], v[40:43]
	v_mfma_f32_16x16x32_bf16 v[96:99], v[230:233], v[234:237], v[20:23]
	v_mfma_f32_16x16x32_bf16 v[20:23], v[206:209], v[238:241], v[44:47]
	v_mfma_f32_16x16x32_bf16 v[88:91], v[222:225], v[242:245], v[20:23]
	v_mfma_f32_16x16x32_bf16 v[20:23], v[226:229], v[238:241], v[48:51]
	v_mfma_f32_16x16x32_bf16 v[80:83], v[230:233], v[242:245], v[20:23]
	v_mfma_f32_16x16x32_bf16 v[20:23], v[206:209], v[246:249], v[52:55]
	v_mfma_f32_16x16x32_bf16 v[60:63], v[222:225], v[250:253], v[20:23]
	v_mfma_f32_16x16x32_bf16 v[20:23], v[226:229], v[246:249], v[182:185]
	v_mfma_f32_16x16x32_bf16 v[124:127], v[222:225], v[28:31], v[68:71]
	v_mfma_f32_16x16x32_bf16 v[48:51], v[230:233], v[250:253], v[20:23]
	s_barrier
	s_mov_b32 m0, s76
	s_nop 2
	v_lshl_add_u64 v[20:21], v[142:143], 0, s[14:15]
	s_add_u32 s38, s40, 0x10080
	ds_read_b128 v[32:35], v145 offset:49152
	ds_read_b128 v[40:43], v145 offset:50176
	ds_read_b128 v[182:185], v145 offset:51200
	ds_read_b128 v[218:221], v145 offset:52224
	ds_read_b128 v[234:237], v145 offset:53248
	ds_read_b128 v[238:241], v145 offset:54272
	ds_read_b128 v[242:245], v145 offset:55296
	ds_read_b128 v[246:249], v145 offset:56320
	global_load_lds_dwordx4 v[20:21], off
	v_lshl_add_u64 v[20:21], v[214:215], 0, s[14:15]
	s_mov_b32 m0, s77
	s_addc_u32 s39, s41, 0
	global_load_lds_dwordx4 v[20:21], off
	v_lshl_add_u64 v[20:21], s[38:39], 0, v[132:133]
	s_mov_b32 m0, s78
	s_nop 0
	global_load_lds_dwordx4 v[20:21], off
	v_lshl_add_u64 v[20:21], s[38:39], 0, v[128:129]
	s_mov_b32 m0, s79
	s_nop 0
	global_load_lds_dwordx4 v[20:21], off
	v_lshl_add_u64 v[20:21], v[148:149], 0, s[14:15]
	s_mov_b32 m0, s51
	s_nop 0
	global_load_lds_dwordx4 v[20:21], off
	v_lshl_add_u64 v[20:21], v[216:217], 0, s[14:15]
	s_mov_b32 m0, s54
	s_nop 0
	global_load_lds_dwordx4 v[20:21], off
	s_waitcnt vmcnt(8)
	s_waitcnt lgkmcnt(0)
	s_barrier
	s_waitcnt lgkmcnt(0)
	v_mfma_f32_16x16x32_bf16 v[20:23], v[12:15], v[32:35], v[150:153]
	v_mfma_f32_16x16x32_bf16 v[76:79], v[16:19], v[40:43], v[20:23]
	v_mfma_f32_16x16x32_bf16 v[20:23], v[178:181], v[32:35], v[154:157]
	v_mfma_f32_16x16x32_bf16 v[68:71], v[202:205], v[40:43], v[20:23]
	v_mfma_f32_16x16x32_bf16 v[20:23], v[12:15], v[182:185], v[158:161]
	v_mfma_f32_16x16x32_bf16 v[44:47], v[16:19], v[218:221], v[20:23]
	v_mfma_f32_16x16x32_bf16 v[20:23], v[178:181], v[182:185], v[162:165]
	v_mfma_f32_16x16x32_bf16 v[36:39], v[202:205], v[218:221], v[20:23]
	v_mfma_f32_16x16x32_bf16 v[20:23], v[12:15], v[234:237], v[166:169]
	v_mfma_f32_16x16x32_bf16 v[0:3], v[12:15], v[242:245], v[0:3]
	v_mfma_f32_16x16x32_bf16 v[28:31], v[16:19], v[238:241], v[20:23]
	v_mfma_f32_16x16x32_bf16 v[20:23], v[178:181], v[234:237], v[170:173]
	v_mfma_f32_16x16x32_bf16 v[12:15], v[16:19], v[246:249], v[0:3]
	v_mfma_f32_16x16x32_bf16 v[0:3], v[178:181], v[242:245], v[4:7]
	v_mfma_f32_16x16x32_bf16 v[20:23], v[202:205], v[238:241], v[20:23]
	v_mfma_f32_16x16x32_bf16 v[4:7], v[202:205], v[246:249], v[0:3]
	v_mfma_f32_16x16x32_bf16 v[0:3], v[206:209], v[32:35], v[8:11]
	v_mfma_f32_16x16x32_bf16 v[72:75], v[222:225], v[40:43], v[0:3]
	v_mfma_f32_16x16x32_bf16 v[0:3], v[226:229], v[32:35], v[210:213]
	v_mfma_f32_16x16x32_bf16 v[52:55], v[230:233], v[40:43], v[0:3]
	v_mfma_f32_16x16x32_bf16 v[0:3], v[206:209], v[182:185], v[24:27]
	v_mfma_f32_16x16x32_bf16 v[40:43], v[222:225], v[218:221], v[0:3]
	v_mfma_f32_16x16x32_bf16 v[0:3], v[226:229], v[182:185], v[186:189]
	v_mfma_f32_16x16x32_bf16 v[32:35], v[230:233], v[218:221], v[0:3]
	v_mfma_f32_16x16x32_bf16 v[0:3], v[206:209], v[234:237], v[190:193]
	v_mfma_f32_16x16x32_bf16 v[24:27], v[222:225], v[238:241], v[0:3]
	v_mfma_f32_16x16x32_bf16 v[0:3], v[226:229], v[234:237], v[194:197]
	v_mfma_f32_16x16x32_bf16 v[16:19], v[230:233], v[238:241], v[0:3]
	v_mfma_f32_16x16x32_bf16 v[0:3], v[206:209], v[242:245], v[198:201]
	v_mfma_f32_16x16x32_bf16 v[8:11], v[222:225], v[246:249], v[0:3]
	v_mfma_f32_16x16x32_bf16 v[0:3], v[226:229], v[242:245], v[174:177]
	v_mfma_f32_16x16x32_bf16 v[0:3], v[230:233], v[246:249], v[0:3]
	s_barrier
	s_andn2_b64 vcc, exec, s[28:29]
	s_cbranch_vccnz .LBB0_388
	s_barrier

.LBB0_404:
	s_setprio 0
	s_cmpk_gt_i32 s26, 0x3fff
	s_barrier
	v_mbcnt_lo_u32_b32 v0, -1, 0
	v_mbcnt_hi_u32_b32 v0, -1, v0
	s_cbranch_scc1 .LBB0_407
	v_and_b32_e32 v2, 64, v254
	v_add_u32_e32 v2, 64, v2
	v_xor_b32_e32 v3, 32, v254
	v_cmp_lt_i32_e32 vcc, v3, v2
	v_readlane_b32 s7, v255, 2
	v_lshlrev_b32_e32 v0, 3, v0
	v_cndmask_b32_e32 v3, v254, v3, vcc
	v_lshlrev_b32_e32 v42, 2, v3
	v_xor_b32_e32 v3, 16, v254
	v_cmp_lt_i32_e32 vcc, v3, v2
	s_lshl_b32 s1, s7, 12
	s_lshl_b32 s6, s2, 4
	v_cndmask_b32_e32 v3, v254, v3, vcc
	v_lshlrev_b32_e32 v43, 2, v3
	v_xor_b32_e32 v3, 8, v254
	v_cmp_lt_i32_e32 vcc, v3, v2
	s_lshl_b32 s7, s7, 1
	v_ashrrev_i32_e32 v1, 31, v0
	v_cndmask_b32_e32 v3, v254, v3, vcc
	v_lshlrev_b32_e32 v44, 2, v3
	v_xor_b32_e32 v3, 4, v254
	v_cmp_lt_i32_e32 vcc, v3, v2
	s_lshl_b32 s0, s2, 15
	s_add_i32 s19, s6, s7
	v_cndmask_b32_e32 v3, v254, v3, vcc
	v_lshlrev_b32_e32 v45, 2, v3
	v_xor_b32_e32 v3, 2, v254
	v_cmp_lt_i32_e32 vcc, v3, v2
	s_mov_b32 s6, 0x3727c5ac
	s_add_i32 s0, s0, s1
	v_cndmask_b32_e32 v3, v254, v3, vcc
	v_lshlrev_b32_e32 v46, 2, v3
	v_xor_b32_e32 v3, 1, v254
	v_cmp_lt_i32_e32 vcc, v3, v2
	s_lshl_b32 s1, s33, 15
	s_lshl_b32 s20, s33, 4
	v_cndmask_b32_e32 v2, v254, v3, vcc
	v_lshlrev_b32_e32 v47, 2, v2
	s_movk_i32 s21, 0x2000
	v_lshlrev_b64 v[32:33], 1, v[0:1]
	s_mov_b64 s[14:15], 0x1000
	s_mov_b64 s[16:17], 0x2000
	s_mov_b32 s18, 0x3b000000
	v_mov_b64_e32 v[34:35], s[6:7]
	s_mov_b32 s22, 0x800000
	s_mov_b32 s23, s26

.LBB0_434:
	ds_read_b128 v[150:153], v147
	ds_read_b128 v[154:157], v147 offset:1024
	ds_read_b128 v[158:161], v147 offset:2048
	ds_read_b128 v[162:165], v147 offset:3072
	ds_read_b128 v[166:169], v148
	ds_read_b128 v[170:173], v148 offset:1024
	ds_read_b128 v[174:177], v148 offset:2048
	ds_read_b128 v[178:181], v148 offset:3072
	s_add_u32 s6, s20, 0x100
	s_addc_u32 s7, s21, 0
	s_cmp_eq_u32 s53, 28
	s_cselect_b32 s25, s17, s7
	s_cselect_b32 s24, s16, s6
	s_cselect_b32 s23, s15, s52
	s_cselect_b32 s22, s50, s51
	v_lshl_add_u64 v[214:215], s[20:21], 0, v[136:137]
	s_add_i32 m0, s36, 0xc000
	ds_read_b128 v[182:185], v149
	ds_read_b128 v[186:189], v149 offset:1024
	ds_read_b128 v[190:193], v149 offset:2048
	ds_read_b128 v[194:197], v149 offset:3072
	ds_read_b128 v[198:201], v149 offset:4096
	ds_read_b128 v[202:205], v149 offset:5120
	ds_read_b128 v[206:209], v149 offset:6144
	ds_read_b128 v[210:213], v149 offset:7168
	global_load_lds_dwordx4 v[214:215], off
	v_lshl_add_u64 v[214:215], s[20:21], 0, v[138:139]
	s_add_i32 m0, s36, 0xe000
	s_nop 0
	global_load_lds_dwordx4 v[214:215], off
	s_waitcnt vmcnt(8)
	s_waitcnt lgkmcnt(0)
	s_barrier
	s_waitcnt lgkmcnt(0)
	v_mfma_f32_16x16x32_bf16 v[124:127], v[150:153], v[182:185], v[124:127]
	v_mfma_f32_16x16x32_bf16 v[120:123], v[158:161], v[182:185], v[120:123]
	v_mfma_f32_16x16x32_bf16 v[116:119], v[150:153], v[190:193], v[116:119]
	v_mfma_f32_16x16x32_bf16 v[112:115], v[158:161], v[190:193], v[112:115]
	v_mfma_f32_16x16x32_bf16 v[100:103], v[150:153], v[198:201], v[100:103]
	v_mfma_f32_16x16x32_bf16 v[96:99], v[158:161], v[198:201], v[96:99]
	v_mfma_f32_16x16x32_bf16 v[84:87], v[150:153], v[206:209], v[84:87]
	v_mfma_f32_16x16x32_bf16 v[80:83], v[158:161], v[206:209], v[80:83]
	v_mfma_f32_16x16x32_bf16 v[124:127], v[154:157], v[186:189], v[124:127]
	v_mfma_f32_16x16x32_bf16 v[120:123], v[162:165], v[186:189], v[120:123]
	v_mfma_f32_16x16x32_bf16 v[116:119], v[154:157], v[194:197], v[116:119]
	v_mfma_f32_16x16x32_bf16 v[112:115], v[162:165], v[194:197], v[112:115]
	v_mfma_f32_16x16x32_bf16 v[100:103], v[154:157], v[202:205], v[100:103]
	v_mfma_f32_16x16x32_bf16 v[96:99], v[162:165], v[202:205], v[96:99]
	v_mfma_f32_16x16x32_bf16 v[84:87], v[154:157], v[210:213], v[84:87]
	v_mfma_f32_16x16x32_bf16 v[80:83], v[162:165], v[210:213], v[80:83]
	v_mfma_f32_16x16x32_bf16 v[108:111], v[166:169], v[182:185], v[108:111]
	v_mfma_f32_16x16x32_bf16 v[104:107], v[174:177], v[182:185], v[104:107]
	v_mfma_f32_16x16x32_bf16 v[92:95], v[166:169], v[190:193], v[92:95]
	v_mfma_f32_16x16x32_bf16 v[88:91], v[174:177], v[190:193], v[88:91]
	v_mfma_f32_16x16x32_bf16 v[76:79], v[166:169], v[198:201], v[76:79]
	v_mfma_f32_16x16x32_bf16 v[72:75], v[174:177], v[198:201], v[72:75]
	v_mfma_f32_16x16x32_bf16 v[68:71], v[166:169], v[206:209], v[68:71]
	v_mfma_f32_16x16x32_bf16 v[64:67], v[174:177], v[206:209], v[64:67]
	v_mfma_f32_16x16x32_bf16 v[108:111], v[170:173], v[186:189], v[108:111]
	v_mfma_f32_16x16x32_bf16 v[104:107], v[178:181], v[186:189], v[104:107]
	v_mfma_f32_16x16x32_bf16 v[92:95], v[170:173], v[194:197], v[92:95]
	v_mfma_f32_16x16x32_bf16 v[88:91], v[178:181], v[194:197], v[88:91]
	v_mfma_f32_16x16x32_bf16 v[76:79], v[170:173], v[202:205], v[76:79]
	v_mfma_f32_16x16x32_bf16 v[72:75], v[178:181], v[202:205], v[72:75]
	v_mfma_f32_16x16x32_bf16 v[68:71], v[170:173], v[210:213], v[68:71]
	v_mfma_f32_16x16x32_bf16 v[64:67], v[178:181], v[210:213], v[64:67]
	s_barrier
	s_add_i32 s20, s44, s3
	v_lshl_add_u64 v[214:215], s[22:23], 0, v[130:131]
	s_mov_b32 m0, s20
	ds_read_b128 v[182:185], v149 offset:16384
	ds_read_b128 v[186:189], v149 offset:17408
	ds_read_b128 v[190:193], v149 offset:18432
	ds_read_b128 v[194:197], v149 offset:19456
	ds_read_b128 v[198:201], v149 offset:20480
	ds_read_b128 v[202:205], v149 offset:21504
	ds_read_b128 v[206:209], v149 offset:22528
	ds_read_b128 v[210:213], v149 offset:23552
	global_load_lds_dwordx4 v[214:215], off
	s_add_i32 m0, s20, 0x2000
	s_add_u32 s20, s22, 0x80000
	v_lshl_add_u64 v[216:217], s[22:23], 0, v[134:135]
	s_addc_u32 s21, s23, 0
	s_add_i32 s54, s45, s3
	global_load_lds_dwordx4 v[216:217], off
	v_lshl_add_u64 v[218:219], s[20:21], 0, v[130:131]
	s_mov_b32 m0, s54
	v_lshl_add_u64 v[220:221], s[24:25], 0, v[132:133]
	global_load_lds_dwordx4 v[218:219], off
	v_lshl_add_u64 v[218:219], s[20:21], 0, v[134:135]
	s_add_i32 m0, s54, 0x2000
	s_nop 0
	global_load_lds_dwordx4 v[218:219], off
	v_lshl_add_u64 v[218:219], s[24:25], 0, v[128:129]
	s_mov_b32 m0, s36
	s_nop 0
	global_load_lds_dwordx4 v[218:219], off
	s_mov_b32 m0, s37
	s_nop 0
	global_load_lds_dwordx4 v[220:221], off
	s_waitcnt vmcnt(8)
	s_waitcnt lgkmcnt(0)
	s_barrier
	s_waitcnt lgkmcnt(0)
	v_mfma_f32_16x16x32_bf16 v[60:63], v[150:153], v[182:185], v[60:63]
	v_mfma_f32_16x16x32_bf16 v[56:59], v[158:161], v[182:185], v[56:59]
	v_mfma_f32_16x16x32_bf16 v[52:55], v[150:153], v[190:193], v[52:55]
	v_mfma_f32_16x16x32_bf16 v[48:51], v[158:161], v[190:193], v[48:51]
	v_mfma_f32_16x16x32_bf16 v[36:39], v[150:153], v[198:201], v[36:39]
	v_mfma_f32_16x16x32_bf16 v[32:35], v[158:161], v[198:201], v[32:35]
	v_mfma_f32_16x16x32_bf16 v[20:23], v[150:153], v[206:209], v[20:23]
	v_mfma_f32_16x16x32_bf16 v[16:19], v[158:161], v[206:209], v[16:19]
	v_mfma_f32_16x16x32_bf16 v[60:63], v[154:157], v[186:189], v[60:63]
	v_mfma_f32_16x16x32_bf16 v[56:59], v[162:165], v[186:189], v[56:59]
	v_mfma_f32_16x16x32_bf16 v[52:55], v[154:157], v[194:197], v[52:55]
	v_mfma_f32_16x16x32_bf16 v[48:51], v[162:165], v[194:197], v[48:51]
	v_mfma_f32_16x16x32_bf16 v[36:39], v[154:157], v[202:205], v[36:39]
	v_mfma_f32_16x16x32_bf16 v[32:35], v[162:165], v[202:205], v[32:35]
	v_mfma_f32_16x16x32_bf16 v[20:23], v[154:157], v[210:213], v[20:23]
	v_mfma_f32_16x16x32_bf16 v[16:19], v[162:165], v[210:213], v[16:19]
	v_mfma_f32_16x16x32_bf16 v[44:47], v[166:169], v[182:185], v[44:47]
	v_mfma_f32_16x16x32_bf16 v[40:43], v[174:177], v[182:185], v[40:43]
	v_mfma_f32_16x16x32_bf16 v[28:31], v[166:169], v[190:193], v[28:31]
	v_mfma_f32_16x16x32_bf16 v[24:27], v[174:177], v[190:193], v[24:27]
	v_mfma_f32_16x16x32_bf16 v[12:15], v[166:169], v[198:201], v[12:15]
	v_mfma_f32_16x16x32_bf16 v[8:11], v[174:177], v[198:201], v[8:11]
	v_mfma_f32_16x16x32_bf16 v[4:7], v[166:169], v[206:209], v[4:7]
	v_mfma_f32_16x16x32_bf16 v[0:3], v[174:177], v[206:209], v[0:3]
	v_mfma_f32_16x16x32_bf16 v[44:47], v[170:173], v[186:189], v[44:47]
	v_mfma_f32_16x16x32_bf16 v[40:43], v[178:181], v[186:189], v[40:43]
	v_mfma_f32_16x16x32_bf16 v[28:31], v[170:173], v[194:197], v[28:31]
	v_mfma_f32_16x16x32_bf16 v[24:27], v[178:181], v[194:197], v[24:27]
	v_mfma_f32_16x16x32_bf16 v[12:15], v[170:173], v[202:205], v[12:15]
	v_mfma_f32_16x16x32_bf16 v[8:11], v[178:181], v[202:205], v[8:11]
	v_mfma_f32_16x16x32_bf16 v[4:7], v[170:173], v[210:213], v[4:7]
	v_mfma_f32_16x16x32_bf16 v[0:3], v[178:181], v[210:213], v[0:3]
	s_barrier
	s_add_i32 s54, 0, 0x18000
	v_add_u32_e32 v162, s54, v145
	v_add_u32_e32 v178, s72, v145
	ds_read_b128 v[150:153], v162
	ds_read_b128 v[154:157], v162 offset:1024
	ds_read_b128 v[158:161], v162 offset:2048
	ds_read_b128 v[162:165], v162 offset:3072
	ds_read_b128 v[166:169], v178
	ds_read_b128 v[170:173], v178 offset:1024
	ds_read_b128 v[174:177], v178 offset:2048
	ds_read_b128 v[178:181], v178 offset:3072
	s_add_u32 s20, s24, 0x180000
	s_addc_u32 s21, s25, 0
	s_mov_b32 m0, s38
	v_lshl_add_u64 v[222:223], s[20:21], 0, v[128:129]
	ds_read_b128 v[182:185], v149 offset:32768
	ds_read_b128 v[186:189], v149 offset:33792
	ds_read_b128 v[190:193], v149 offset:34816
	ds_read_b128 v[194:197], v149 offset:35840
	ds_read_b128 v[198:201], v149 offset:36864
	ds_read_b128 v[202:205], v149 offset:37888
	ds_read_b128 v[206:209], v149 offset:38912
	ds_read_b128 v[210:213], v149 offset:39936
	global_load_lds_dwordx4 v[222:223], off
	v_lshl_add_u64 v[222:223], s[20:21], 0, v[132:133]
	s_mov_b32 m0, s39
	s_nop 0
	global_load_lds_dwordx4 v[222:223], off
	s_waitcnt vmcnt(8)
	s_waitcnt lgkmcnt(0)
	s_barrier
	s_waitcnt lgkmcnt(0)
	v_mfma_f32_16x16x32_bf16 v[124:127], v[150:153], v[182:185], v[124:127]
	v_mfma_f32_16x16x32_bf16 v[120:123], v[158:161], v[182:185], v[120:123]
	v_mfma_f32_16x16x32_bf16 v[116:119], v[150:153], v[190:193], v[116:119]
	v_mfma_f32_16x16x32_bf16 v[112:115], v[158:161], v[190:193], v[112:115]
	v_mfma_f32_16x16x32_bf16 v[100:103], v[150:153], v[198:201], v[100:103]
	v_mfma_f32_16x16x32_bf16 v[96:99], v[158:161], v[198:201], v[96:99]
	v_mfma_f32_16x16x32_bf16 v[84:87], v[150:153], v[206:209], v[84:87]
	v_mfma_f32_16x16x32_bf16 v[80:83], v[158:161], v[206:209], v[80:83]
	v_mfma_f32_16x16x32_bf16 v[124:127], v[154:157], v[186:189], v[124:127]
	v_mfma_f32_16x16x32_bf16 v[120:123], v[162:165], v[186:189], v[120:123]
	v_mfma_f32_16x16x32_bf16 v[116:119], v[154:157], v[194:197], v[116:119]
	v_mfma_f32_16x16x32_bf16 v[112:115], v[162:165], v[194:197], v[112:115]
	v_mfma_f32_16x16x32_bf16 v[100:103], v[154:157], v[202:205], v[100:103]
	v_mfma_f32_16x16x32_bf16 v[96:99], v[162:165], v[202:205], v[96:99]
	v_mfma_f32_16x16x32_bf16 v[84:87], v[154:157], v[210:213], v[84:87]
	v_mfma_f32_16x16x32_bf16 v[80:83], v[162:165], v[210:213], v[80:83]
	v_mfma_f32_16x16x32_bf16 v[108:111], v[166:169], v[182:185], v[108:111]
	v_mfma_f32_16x16x32_bf16 v[104:107], v[174:177], v[182:185], v[104:107]
	v_mfma_f32_16x16x32_bf16 v[92:95], v[166:169], v[190:193], v[92:95]
	v_mfma_f32_16x16x32_bf16 v[88:91], v[174:177], v[190:193], v[88:91]
	v_mfma_f32_16x16x32_bf16 v[76:79], v[166:169], v[198:201], v[76:79]
	v_mfma_f32_16x16x32_bf16 v[72:75], v[174:177], v[198:201], v[72:75]
	v_mfma_f32_16x16x32_bf16 v[68:71], v[166:169], v[206:209], v[68:71]
	v_mfma_f32_16x16x32_bf16 v[64:67], v[174:177], v[206:209], v[64:67]
	v_mfma_f32_16x16x32_bf16 v[108:111], v[170:173], v[186:189], v[108:111]
	v_mfma_f32_16x16x32_bf16 v[104:107], v[178:181], v[186:189], v[104:107]
	v_mfma_f32_16x16x32_bf16 v[92:95], v[170:173], v[194:197], v[92:95]
	v_mfma_f32_16x16x32_bf16 v[88:91], v[178:181], v[194:197], v[88:91]
	v_mfma_f32_16x16x32_bf16 v[76:79], v[170:173], v[202:205], v[76:79]
	v_mfma_f32_16x16x32_bf16 v[72:75], v[178:181], v[202:205], v[72:75]
	v_mfma_f32_16x16x32_bf16 v[68:71], v[170:173], v[210:213], v[68:71]
	v_mfma_f32_16x16x32_bf16 v[64:67], v[178:181], v[210:213], v[64:67]
	s_barrier
	s_add_i32 s20, s54, s3
	v_lshl_add_u64 v[214:215], v[214:215], 0, s[12:13]
	s_mov_b32 m0, s20
	ds_read_b128 v[182:185], v149 offset:49152
	ds_read_b128 v[186:189], v149 offset:50176
	ds_read_b128 v[190:193], v149 offset:51200
	ds_read_b128 v[194:197], v149 offset:52224
	ds_read_b128 v[198:201], v149 offset:53248
	ds_read_b128 v[202:205], v149 offset:54272
	ds_read_b128 v[206:209], v149 offset:55296
	ds_read_b128 v[210:213], v149 offset:56320
	global_load_lds_dwordx4 v[214:215], off
	s_add_i32 m0, s20, 0x2000
	s_add_u32 s20, s22, 0x80080
	v_lshl_add_u64 v[214:215], v[216:217], 0, s[12:13]
	s_addc_u32 s21, s23, 0
	s_add_i32 s22, s72, s3
	global_load_lds_dwordx4 v[214:215], off
	v_lshl_add_u64 v[214:215], s[20:21], 0, v[130:131]
	s_mov_b32 m0, s22
	s_nop 0
	global_load_lds_dwordx4 v[214:215], off
	v_lshl_add_u64 v[214:215], s[20:21], 0, v[134:135]
	s_add_i32 m0, s22, 0x2000
	s_nop 0
	global_load_lds_dwordx4 v[214:215], off
	v_lshl_add_u64 v[214:215], v[218:219], 0, s[12:13]
	s_mov_b32 m0, s41
	s_nop 0
	global_load_lds_dwordx4 v[214:215], off
	v_lshl_add_u64 v[214:215], v[220:221], 0, s[12:13]
	s_mov_b32 m0, s42
	s_nop 0
	global_load_lds_dwordx4 v[214:215], off
	s_waitcnt vmcnt(8)
	s_waitcnt lgkmcnt(0)
	s_barrier
	s_waitcnt lgkmcnt(0)
	v_mfma_f32_16x16x32_bf16 v[60:63], v[150:153], v[182:185], v[60:63]
	v_mfma_f32_16x16x32_bf16 v[56:59], v[158:161], v[182:185], v[56:59]
	v_mfma_f32_16x16x32_bf16 v[52:55], v[150:153], v[190:193], v[52:55]
	v_mfma_f32_16x16x32_bf16 v[48:51], v[158:161], v[190:193], v[48:51]
	v_mfma_f32_16x16x32_bf16 v[36:39], v[150:153], v[198:201], v[36:39]
	v_mfma_f32_16x16x32_bf16 v[32:35], v[158:161], v[198:201], v[32:35]
	v_mfma_f32_16x16x32_bf16 v[20:23], v[150:153], v[206:209], v[20:23]
	v_mfma_f32_16x16x32_bf16 v[16:19], v[158:161], v[206:209], v[16:19]
	v_mfma_f32_16x16x32_bf16 v[60:63], v[154:157], v[186:189], v[60:63]
	v_mfma_f32_16x16x32_bf16 v[56:59], v[162:165], v[186:189], v[56:59]
	v_mfma_f32_16x16x32_bf16 v[52:55], v[154:157], v[194:197], v[52:55]
	v_mfma_f32_16x16x32_bf16 v[48:51], v[162:165], v[194:197], v[48:51]
	v_mfma_f32_16x16x32_bf16 v[36:39], v[154:157], v[202:205], v[36:39]
	v_mfma_f32_16x16x32_bf16 v[32:35], v[162:165], v[202:205], v[32:35]
	v_mfma_f32_16x16x32_bf16 v[20:23], v[154:157], v[210:213], v[20:23]
	v_mfma_f32_16x16x32_bf16 v[16:19], v[162:165], v[210:213], v[16:19]
	v_mfma_f32_16x16x32_bf16 v[44:47], v[166:169], v[182:185], v[44:47]
	v_mfma_f32_16x16x32_bf16 v[40:43], v[174:177], v[182:185], v[40:43]
	v_mfma_f32_16x16x32_bf16 v[28:31], v[166:169], v[190:193], v[28:31]
	v_mfma_f32_16x16x32_bf16 v[24:27], v[174:177], v[190:193], v[24:27]
	v_mfma_f32_16x16x32_bf16 v[12:15], v[166:169], v[198:201], v[12:15]
	v_mfma_f32_16x16x32_bf16 v[8:11], v[174:177], v[198:201], v[8:11]
	v_mfma_f32_16x16x32_bf16 v[4:7], v[166:169], v[206:209], v[4:7]
	v_mfma_f32_16x16x32_bf16 v[0:3], v[174:177], v[206:209], v[0:3]
	v_mfma_f32_16x16x32_bf16 v[44:47], v[170:173], v[186:189], v[44:47]
	v_mfma_f32_16x16x32_bf16 v[40:43], v[178:181], v[186:189], v[40:43]
	v_mfma_f32_16x16x32_bf16 v[28:31], v[170:173], v[194:197], v[28:31]
	v_mfma_f32_16x16x32_bf16 v[24:27], v[178:181], v[194:197], v[24:27]
	v_mfma_f32_16x16x32_bf16 v[12:15], v[170:173], v[202:205], v[12:15]
	v_mfma_f32_16x16x32_bf16 v[8:11], v[178:181], v[202:205], v[8:11]
	v_mfma_f32_16x16x32_bf16 v[4:7], v[170:173], v[210:213], v[4:7]
	v_mfma_f32_16x16x32_bf16 v[0:3], v[178:181], v[210:213], v[0:3]
	s_barrier
	s_add_i32 s53, s53, 2
	s_add_u32 s51, s51, 0x100
	s_addc_u32 s52, s52, 0
	s_cmp_gt_u32 s53, 29
	s_mov_b64 s[20:21], s[6:7]
	s_cbranch_scc0 .LBB0_434
	s_and_b64 vcc, exec, s[28:29]
	s_cbranch_vccz .LBB0_437
	s_barrier

.LBB0_449:
	s_setprio 0
	s_and_b64 vcc, exec, s[8:9]
	s_barrier
	v_mbcnt_lo_u32_b32 v0, -1, 0
	v_mbcnt_hi_u32_b32 v0, -1, v0
	s_cbranch_vccnz .LBB0_454
	v_lshlrev_b32_e32 v16, 2, v0
	v_and_b32_e32 v0, 64, v254
	v_add_u32_e32 v0, 64, v0
	v_xor_b32_e32 v1, 32, v254
	v_cmp_lt_i32_e32 vcc, v1, v0
	v_ashrrev_i32_e32 v17, 31, v16
	v_readlane_b32 s4, v255, 3
	v_cndmask_b32_e32 v1, v254, v1, vcc
	v_lshlrev_b32_e32 v46, 2, v1
	v_xor_b32_e32 v1, 16, v254
	v_cmp_lt_i32_e32 vcc, v1, v0
	v_lshlrev_b64 v[20:21], 2, v[16:17]
	v_readlane_b32 s14, v255, 13
	v_cndmask_b32_e32 v1, v254, v1, vcc
	v_lshlrev_b32_e32 v47, 2, v1
	v_xor_b32_e32 v1, 8, v254
	v_cmp_lt_i32_e32 vcc, v1, v0
	v_readlane_b32 s15, v255, 14
	s_mov_b64 s[2:3], 0x1000
	v_cndmask_b32_e32 v1, v254, v1, vcc
	v_lshlrev_b32_e32 v48, 2, v1
	v_xor_b32_e32 v1, 4, v254
	v_cmp_lt_i32_e32 vcc, v1, v0
	v_lshl_add_u64 v[2:3], s[14:15], 0, v[20:21]
	s_lshl_b32 s0, s33, 4
	v_cndmask_b32_e32 v1, v254, v1, vcc
	v_lshlrev_b32_e32 v49, 2, v1
	v_xor_b32_e32 v1, 2, v254
	v_lshl_add_u64 v[24:25], v[2:3], 0, s[2:3]
	s_ashr_i32 s27, s26, 31
	s_mul_i32 s2, s26, 0x3000
	v_cmp_lt_i32_e32 vcc, v1, v0
	s_mul_hi_i32 s1, s26, 0x3000
	s_add_u32 s2, s62, s2
	v_cndmask_b32_e32 v1, v254, v1, vcc
	v_readlane_b32 s5, v255, 4
	s_addc_u32 s3, s63, s1
	s_add_i32 s4, s26, s82
	v_lshlrev_b32_e32 v50, 2, v1
	v_xor_b32_e32 v1, 1, v254
	s_ashr_i32 s5, s4, 31
	v_cmp_lt_i32_e32 vcc, v1, v0
	s_ashr_i32 s1, s0, 31
	s_lshl_b64 s[4:5], s[4:5], 12
	v_cndmask_b32_e32 v0, v254, v1, vcc
	v_readlane_b32 s6, v255, 5
	v_readlane_b32 s7, v255, 6
	v_readlane_b32 s8, v255, 7
	v_readlane_b32 s9, v255, 8
	s_add_u32 s4, s30, s4
	v_lshlrev_b32_e32 v51, 2, v0
	v_lshlrev_b64 v[0:1], 1, v[16:17]
	s_addc_u32 s5, s31, s5
	s_lshl_b64 s[6:7], s[0:1], 12
	s_lshl_b64 s[8:9], s[26:27], 12
	v_lshl_add_u64 v[18:19], s[62:63], 0, v[0:1]
	v_readlane_b32 s10, v255, 9
	v_readlane_b32 s11, v255, 10
	v_readlane_b32 s16, v255, 15
	v_lshl_add_u64 v[0:1], s[2:3], 0, v[0:1]
	s_mov_b64 s[2:3], 0x400
	s_add_u32 s8, s30, s8
	v_lshl_add_u64 v[22:23], s[30:31], 0, v[20:21]
	v_lshl_add_u64 v[26:27], v[0:1], 0, s[2:3]
	s_mul_i32 s2, s33, 0x30000
	s_mul_hi_i32 s3, s0, 0x3000
	s_addc_u32 s9, s31, s9
	v_mov_b32_e32 v52, 0x3000
	s_mov_b64 s[10:11], 0xe000
	s_mov_b32 s1, 0xe000
	v_mov_b32_e32 v53, 0x358637bd
	s_mov_b32 s16, 0x800000
	v_readlane_b32 s12, v255, 11
	v_readlane_b32 s13, v255, 12
	v_readlane_b32 s17, v255, 16
	v_readlane_b32 s18, v255, 17
	v_readlane_b32 s19, v255, 18
	s_branch .LBB0_452
